# v18: FFN-up epilogue conv halo shuffles via DPP row_shr/row_ror instead of 128 ds_bpermute round trips per unit
# speedup vs baseline: 1.0138x; 1.0032x over previous
; DI float silu_f(float x) { return x * __builtin_amdgcn_rcpf(1.f + __builtin_amdgcn_exp2f(-LOG2E * x)); }
; DI float rstd_of(float ssq, float inv_n) { return 1.0f / sqrtf(ssq * inv_n + EPS); }
; DI float acc_get_i(const acc_t* base, unsigned idx, float inv_scale) { return (float)(*(const acc_t*)((const char*)base + idx * 8u)) * inv_scale; }
;     DI void operator()(const f32x4 (&acc)[2][2][4][2], const Unit& u, int wr, int wc, int fr, int fq) const {
;     ...
;             const int c4 = c8 + 4 * n;
;             const f32x4 w0 = *(const f32x4*)(cw + c4), w1 = *(const f32x4*)(cw + DFF + c4), w2 = *(const f32x4*)(cw + 2 * DFF + c4), cbv = *(const f32x4*)(cb + c4);
; #pragma unroll
;             for (int ai = 0; ai < 2; ++ai) {
;                 f32x4 pg = {0.f, 0.f, 0.f, 0.f};
; #pragma unroll
;                 for (int m = 0; m < 4; ++m) { const int row = u.pm * BM + ai * HALF + wr * 64 + m * 16 + fr;
;                     const float rs = rstd_of(acc_get_i(ssq, (unsigned)row, 1.0f / SSQ_SCALE), 1.0f / DM);
;                     const f32x4 g = acc[ai][0][m][n] * rs, up = acc[ai][1][m][n] * rs;
;                     f32x4 a;
; #pragma unroll
;                     for (int j = 0; j < 4; ++j) { const float s1 = __shfl(fr == 15 ? pg[j] : g[j], src1), s2 = __shfl(fr >= 14 ? pg[j] : g[j], src2);
;                         a[j] = silu_f(cbv[j] + w0[j] * s2 + w1[j] * s1 + w2[j] * g[j]) * up[j]; }
.LBB0_3093:
	s_lshl_b32 s15, s0, 8
	s_add_i32 s15, s15, s80
	v_or_b32_e32 v194, s15, v209
	v_lshlrev_b32_e32 v96, 3, v194
	v_lshlrev_b64 v[142:143], 2, v[176:177]
	v_lshl_add_u64 v[178:179], s[54:55], 0, v[142:143]
	v_lshl_add_u64 v[134:135], s[62:63], 0, v[142:143]
	v_lshl_add_u64 v[138:139], s[64:65], 0, v[142:143]
	v_lshl_add_u64 v[180:181], s[56:57], 0, v[142:143]
	global_load_dwordx4 v[130:133], v[178:179], off
	global_load_dwordx4 v[142:145], v[180:181], off
	v_mul_lo_u32 v218, v194, s90
	global_load_dwordx4 v[134:137], v[134:135], off
	global_load_dwordx2 v[236:237], v96, s[48:49]
	global_load_dwordx2 v[238:239], v96, s[48:49] offset:128
	global_load_dwordx2 v[240:241], v96, s[48:49] offset:256
	global_load_dwordx2 v[242:243], v96, s[48:49] offset:384
	global_load_dwordx2 v[246:247], v96, s[48:49] offset:1024
	global_load_dwordx2 v[250:251], v96, s[48:49] offset:1152
	global_load_dwordx2 v[146:147], v96, s[48:49] offset:1280
	global_load_dwordx2 v[148:149], v96, s[48:49] offset:1408
	s_waitcnt vmcnt(0)
	v_ffbh_u32_e32 v150, v237
	v_min_u32_e32 v150, 32, v150
	v_lshlrev_b64 v[236:237], v150, v[236:237]
	v_min_u32_e32 v236, 1, v236
	v_or_b32_e32 v236, v237, v236
	v_cvt_f32_u32_e32 v236, v236
	v_sub_u32_e32 v237, 32, v150
	v_ldexp_f32 v236, v236, v237
	v_mul_f32_e32 v236, 0x35800000, v236
	v_fmamk_f32 v236, v236, 0x3a800000, v222
	v_rsq_f32_e32 v237, v236
	s_nop 0
	v_mul_f32_e32 v150, v236, v237
	v_fma_f32 v150, -v150, v237, 1.0
	v_mul_f32_e32 v150, 0.5, v150
	v_fmac_f32_e32 v237, v150, v237
	v_ffbh_u32_e32 v150, v239
	v_min_u32_e32 v150, 32, v150
	v_lshlrev_b64 v[238:239], v150, v[238:239]
	v_min_u32_e32 v238, 1, v238
	v_or_b32_e32 v238, v239, v238
	v_cvt_f32_u32_e32 v238, v238
	v_sub_u32_e32 v239, 32, v150
	v_ldexp_f32 v238, v238, v239
	v_mul_f32_e32 v238, 0x35800000, v238
	v_fmamk_f32 v238, v238, 0x3a800000, v222
	v_rsq_f32_e32 v239, v238
	s_nop 0
	v_mul_f32_e32 v150, v238, v239
	v_fma_f32 v150, -v150, v239, 1.0
	v_mul_f32_e32 v150, 0.5, v150
	v_fmac_f32_e32 v239, v150, v239
	v_ffbh_u32_e32 v150, v241
	v_min_u32_e32 v150, 32, v150
	v_lshlrev_b64 v[240:241], v150, v[240:241]
	v_min_u32_e32 v240, 1, v240
	v_or_b32_e32 v240, v241, v240
	v_cvt_f32_u32_e32 v240, v240
	v_sub_u32_e32 v241, 32, v150
	v_ldexp_f32 v240, v240, v241
	v_mul_f32_e32 v240, 0x35800000, v240
	v_fmamk_f32 v240, v240, 0x3a800000, v222
	v_rsq_f32_e32 v241, v240
	s_nop 0
	v_mul_f32_e32 v150, v240, v241
	v_fma_f32 v150, -v150, v241, 1.0
	v_mul_f32_e32 v150, 0.5, v150
	v_fmac_f32_e32 v241, v150, v241
	v_ffbh_u32_e32 v150, v243
	v_min_u32_e32 v150, 32, v150
	v_lshlrev_b64 v[242:243], v150, v[242:243]
	v_min_u32_e32 v242, 1, v242
	v_or_b32_e32 v242, v243, v242
	v_cvt_f32_u32_e32 v242, v242
	v_sub_u32_e32 v243, 32, v150
	v_ldexp_f32 v242, v242, v243
	v_mul_f32_e32 v242, 0x35800000, v242
	v_fmamk_f32 v242, v242, 0x3a800000, v222
	v_rsq_f32_e32 v243, v242
	s_nop 0
	v_mul_f32_e32 v150, v242, v243
	v_fma_f32 v150, -v150, v243, 1.0
	v_mul_f32_e32 v150, 0.5, v150
	v_fmac_f32_e32 v243, v150, v243
	v_ffbh_u32_e32 v150, v247
	v_min_u32_e32 v150, 32, v150
	v_lshlrev_b64 v[246:247], v150, v[246:247]
	v_min_u32_e32 v246, 1, v246
	v_or_b32_e32 v246, v247, v246
	v_cvt_f32_u32_e32 v246, v246
	v_sub_u32_e32 v247, 32, v150
	v_ldexp_f32 v246, v246, v247
	v_mul_f32_e32 v246, 0x35800000, v246
	v_fmamk_f32 v246, v246, 0x3a800000, v222
	v_rsq_f32_e32 v247, v246
	s_nop 0
	v_mul_f32_e32 v150, v246, v247
	v_fma_f32 v150, -v150, v247, 1.0
	v_mul_f32_e32 v150, 0.5, v150
	v_fmac_f32_e32 v247, v150, v247
	v_ffbh_u32_e32 v150, v251
	v_min_u32_e32 v150, 32, v150
	v_lshlrev_b64 v[250:251], v150, v[250:251]
	v_min_u32_e32 v250, 1, v250
	v_or_b32_e32 v250, v251, v250
	v_cvt_f32_u32_e32 v250, v250
	v_sub_u32_e32 v251, 32, v150
	v_ldexp_f32 v250, v250, v251
	v_mul_f32_e32 v250, 0x35800000, v250
	v_fmamk_f32 v250, v250, 0x3a800000, v222
	v_rsq_f32_e32 v251, v250
	s_nop 0
	v_mul_f32_e32 v150, v250, v251
	v_fma_f32 v150, -v150, v251, 1.0
	v_mul_f32_e32 v150, 0.5, v150
	v_fmac_f32_e32 v251, v150, v251
	v_ffbh_u32_e32 v150, v147
	v_min_u32_e32 v150, 32, v150
	v_lshlrev_b64 v[146:147], v150, v[146:147]
	v_min_u32_e32 v146, 1, v146
	v_or_b32_e32 v146, v147, v146
	v_cvt_f32_u32_e32 v146, v146
	v_sub_u32_e32 v147, 32, v150
	v_ldexp_f32 v146, v146, v147
	v_mul_f32_e32 v146, 0x35800000, v146
	v_fmamk_f32 v146, v146, 0x3a800000, v222
	v_rsq_f32_e32 v147, v146
	s_nop 0
	v_mul_f32_e32 v150, v146, v147
	v_fma_f32 v150, -v150, v147, 1.0
	v_mul_f32_e32 v150, 0.5, v150
	v_fmac_f32_e32 v147, v150, v147
	v_ffbh_u32_e32 v150, v149
	v_min_u32_e32 v150, 32, v150
	v_lshlrev_b64 v[148:149], v150, v[148:149]
	v_min_u32_e32 v148, 1, v148
	v_or_b32_e32 v148, v149, v148
	v_cvt_f32_u32_e32 v148, v148
	v_sub_u32_e32 v149, 32, v150
	v_ldexp_f32 v148, v148, v149
	v_mul_f32_e32 v148, 0x35800000, v148
	v_fmamk_f32 v148, v148, 0x3a800000, v222
	v_rsq_f32_e32 v149, v148
	s_nop 0
	v_mul_f32_e32 v150, v148, v149
	v_fma_f32 v150, -v150, v149, 1.0
	v_mul_f32_e32 v150, 0.5, v150
	v_fmac_f32_e32 v149, v150, v149
	v_mov_b32_e32 v236, v237
	v_mov_b32_e32 v237, v239
	v_mov_b32_e32 v238, v241
	v_mov_b32_e32 v239, v243
	v_mov_b32_e32 v240, v247
	v_mov_b32_e32 v241, v251
	v_mov_b32_e32 v242, v147
	v_mov_b32_e32 v243, v149
	s_waitcnt vmcnt(0)
	global_load_dwordx4 v[138:141], v[138:139], off
	v_mov_b32_e32 v148, v236
	v_pk_mul_f32 v[186:187], v[126:127], v[148:149] op_sel_hi:[1,0]
	v_pk_mul_f32 v[184:185], v[128:129], v[148:149] op_sel_hi:[1,0]
	v_mov_b32_e32 v188, 0
	v_mov_b32_dpp v188, v186 row_shr:1 row_mask:0xf bank_mask:0xf
	v_mov_b32_e32 v192, 0
	v_mov_b32_dpp v192, v186 row_shr:2 row_mask:0xf bank_mask:0xf
	v_mov_b32_e32 v189, 0
	v_mov_b32_dpp v189, v187 row_shr:1 row_mask:0xf bank_mask:0xf
	v_mov_b32_e32 v193, 0
	v_mov_b32_dpp v193, v187 row_shr:2 row_mask:0xf bank_mask:0xf
	v_mov_b32_e32 v182, 0
	v_mov_b32_dpp v182, v184 row_shr:1 row_mask:0xf bank_mask:0xf
	v_mov_b32_e32 v190, 0
	v_mov_b32_dpp v190, v184 row_shr:2 row_mask:0xf bank_mask:0xf
	v_mov_b32_e32 v183, 0
	v_mov_b32_dpp v183, v185 row_shr:1 row_mask:0xf bank_mask:0xf
	v_mov_b32_e32 v191, 0
	v_mov_b32_dpp v191, v185 row_shr:2 row_mask:0xf bank_mask:0xf
	v_pk_mul_f32 v[146:147], v[120:121], v[148:149] op_sel_hi:[1,0]
	v_pk_mul_f32 v[148:149], v[118:119], v[148:149] op_sel_hi:[1,0]
	s_and_saveexec_b64 s[0:1], s[40:41]
	s_xor_b64 s[0:1], exec, s[0:1]
	s_cbranch_execz .LBB0_3095
; DI unsigned pk2(float lo, float hi) { f32x2 v = {lo, hi}; bf16x2_t b = __builtin_convertvector(v, bf16x2_t); return __builtin_bit_cast(unsigned, b); }
; DI float silu_f(float x) { return x * __builtin_amdgcn_rcpf(1.f + __builtin_amdgcn_exp2f(-LOG2E * x)); }
; template <class T> DI T* boff(T* base, unsigned byte_off) { return (T*)((char*)base + byte_off); }
;     DI void operator()(const f32x4 (&acc)[2][2][4][2], const Unit& u, int wr, int wc, int fr, int fq) const {
;     ...
;                     for (int j = 0; j < 4; ++j) { const float s1 = __shfl(fr == 15 ? pg[j] : g[j], src1), s2 = __shfl(fr >= 14 ? pg[j] : g[j], src2);
;                         a[j] = silu_f(cbv[j] + w0[j] * s2 + w1[j] * s1 + w2[j] * g[j]) * up[j]; }
;                     u32x2 gw; gw.x = pk2(g[0], g[1]); gw.y = pk2(g[2], g[3]);
;                     if (m == 0 && fr < 2) {
;                         *boff((u32x2*)GS, (unsigned)(((row >> 6) * 4 + 2 + fr) * DFF + c4) * 2u) = gw;
;                         u32x2 uw; uw.x = pk2(up[0], up[1]); uw.y = pk2(up[2], up[3]); *boff((u32x2*)US, (unsigned)(((row >> 6) * 2 + fr) * DFF + c4) * 2u) = uw;
;                     } else { u32x2 w; w.x = pk2(a[0], a[1]); w.y = pk2(a[2], a[3]); *boff((u32x2*)A2, (unsigned)(row * DFF + c4) * 2u) = w; }
	s_waitcnt lgkmcnt(4)
	v_pk_fma_f32 v[150:151], v[130:131], v[192:193], v[142:143]
	s_nop 0
	v_pk_fma_f32 v[150:151], v[134:135], v[188:189], v[150:151]
	s_waitcnt lgkmcnt(0)
	v_pk_fma_f32 v[188:189], v[132:133], v[190:191], v[144:145]
	s_waitcnt vmcnt(0)
	v_pk_fma_f32 v[150:151], v[138:139], v[186:187], v[150:151]
	v_pk_fma_f32 v[182:183], v[136:137], v[182:183], v[188:189]
	v_mul_f32_e32 v152, 0xbfb8aa3b, v150
	v_mul_f32_e32 v153, 0xbfb8aa3b, v151
	v_pk_fma_f32 v[182:183], v[140:141], v[184:185], v[182:183]
	v_exp_f32_e32 v152, v152
	v_exp_f32_e32 v153, v153
	v_mul_f32_e32 v188, 0xbfb8aa3b, v182
	v_mul_f32_e32 v189, 0xbfb8aa3b, v183
	v_exp_f32_e32 v188, v188
	v_exp_f32_e32 v189, v189
	v_add_f32_e32 v152, 1.0, v152
	v_add_f32_e32 v153, 1.0, v153
	v_rcp_f32_e32 v152, v152
	v_rcp_f32_e32 v153, v153
	v_add_f32_e32 v188, 1.0, v188
	v_add_f32_e32 v189, 1.0, v189
	v_rcp_f32_e32 v188, v188
	v_rcp_f32_e32 v189, v189
	v_pk_mul_f32 v[150:151], v[150:151], v[152:153]
	s_nop 0
	v_pk_mul_f32 v[148:149], v[148:149], v[150:151]
	v_pk_mul_f32 v[150:151], v[182:183], v[188:189]
	v_cvt_pk_bf16_f32 v148, v148, v149
	v_pk_mul_f32 v[146:147], v[146:147], v[150:151]
	s_nop 0
	v_cvt_pk_bf16_f32 v149, v146, v147
	v_add_lshl_u32 v146, v218, v176, 1
	global_store_dwordx2 v146, v[148:149], s[46:47]

; DI unsigned pk2(float lo, float hi) { f32x2 v = {lo, hi}; bf16x2_t b = __builtin_convertvector(v, bf16x2_t); return __builtin_bit_cast(unsigned, b); }
; DI float silu_f(float x) { return x * __builtin_amdgcn_rcpf(1.f + __builtin_amdgcn_exp2f(-LOG2E * x)); }
; DI float rstd_of(float ssq, float inv_n) { return 1.0f / sqrtf(ssq * inv_n + EPS); }
; DI float acc_get_i(const acc_t* base, unsigned idx, float inv_scale) { return (float)(*(const acc_t*)((const char*)base + idx * 8u)) * inv_scale; }
; template <class T> DI T* boff(T* base, unsigned byte_off) { return (T*)((char*)base + byte_off); }
;     DI void operator()(const f32x4 (&acc)[2][2][4][2], const Unit& u, int wr, int wc, int fr, int fq) const {
;     ...
;                 for (int m = 0; m < 4; ++m) { const int row = u.pm * BM + ai * HALF + wr * 64 + m * 16 + fr;
;                     const float rs = rstd_of(acc_get_i(ssq, (unsigned)row, 1.0f / SSQ_SCALE), 1.0f / DM);
;                     const f32x4 g = acc[ai][0][m][n] * rs, up = acc[ai][1][m][n] * rs;
;                     f32x4 a;
; #pragma unroll
;                     for (int j = 0; j < 4; ++j) { const float s1 = __shfl(fr == 15 ? pg[j] : g[j], src1), s2 = __shfl(fr >= 14 ? pg[j] : g[j], src2);
;                         a[j] = silu_f(cbv[j] + w0[j] * s2 + w1[j] * s1 + w2[j] * g[j]) * up[j]; }
;                     u32x2 gw; gw.x = pk2(g[0], g[1]); gw.y = pk2(g[2], g[3]);
;                     if (m == 0 && fr < 2) {
;                         *boff((u32x2*)GS, (unsigned)(((row >> 6) * 4 + 2 + fr) * DFF + c4) * 2u) = gw;
;                         u32x2 uw; uw.x = pk2(up[0], up[1]); uw.y = pk2(up[2], up[3]); *boff((u32x2*)US, (unsigned)(((row >> 6) * 2 + fr) * DFF + c4) * 2u) = uw;
;                     } else { u32x2 w; w.x = pk2(a[0], a[1]); w.y = pk2(a[2], a[3]); *boff((u32x2*)A2, (unsigned)(row * DFF + c4) * 2u) = w; }
.LBB0_3097:
	s_or_b64 exec, exec, s[0:1]
	v_or_b32_e32 v192, 16, v194
	v_add_u32_e32 v146, s2, v212
	v_lshlrev_b32_e32 v182, 3, v192
	v_mul_lo_u32 v217, v146, s90
	s_ashr_i32 s0, s15, 10
	s_and_b32 s14, s0, 0x3ffffffe
	s_add_i32 s14, s14, 0x3ffff802
	v_mov_b32_e32 v150, v237
	v_pk_mul_f32 v[148:149], v[110:111], v[150:151] op_sel_hi:[1,0]
	v_pk_mul_f32 v[146:147], v[112:113], v[150:151] op_sel_hi:[1,0]
	v_mov_b32_dpp v152, v186 row_ror:1 row_mask:0xf bank_mask:0xf
	v_mov_b32_dpp v152, v148 row_shr:1 row_mask:0xf bank_mask:0xf
	v_mov_b32_dpp v186, v186 row_ror:2 row_mask:0xf bank_mask:0xf
	v_mov_b32_dpp v186, v148 row_shr:2 row_mask:0xf bank_mask:0xf
	v_mov_b32_dpp v153, v187 row_ror:1 row_mask:0xf bank_mask:0xf
	v_mov_b32_dpp v153, v149 row_shr:1 row_mask:0xf bank_mask:0xf
	v_mov_b32_dpp v187, v187 row_ror:2 row_mask:0xf bank_mask:0xf
	v_mov_b32_dpp v187, v149 row_shr:2 row_mask:0xf bank_mask:0xf
	v_mov_b32_dpp v188, v184 row_ror:1 row_mask:0xf bank_mask:0xf
	v_mov_b32_dpp v188, v146 row_shr:1 row_mask:0xf bank_mask:0xf
	v_mov_b32_dpp v184, v184 row_ror:2 row_mask:0xf bank_mask:0xf
	v_mov_b32_dpp v184, v146 row_shr:2 row_mask:0xf bank_mask:0xf
	s_waitcnt lgkmcnt(2)
	v_pk_fma_f32 v[186:187], v[130:131], v[186:187], v[142:143]
	v_mov_b32_dpp v189, v185 row_ror:1 row_mask:0xf bank_mask:0xf
	v_mov_b32_dpp v189, v147 row_shr:1 row_mask:0xf bank_mask:0xf
	v_pk_fma_f32 v[152:153], v[134:135], v[152:153], v[186:187]
	v_pk_fma_f32 v[152:153], v[138:139], v[148:149], v[152:153]
	v_mov_b32_dpp v185, v185 row_ror:2 row_mask:0xf bank_mask:0xf
	v_mov_b32_dpp v185, v147 row_shr:2 row_mask:0xf bank_mask:0xf
	v_mul_f32_e32 v186, 0xbfb8aa3b, v152
	v_mul_f32_e32 v187, 0xbfb8aa3b, v153
	v_exp_f32_e32 v186, v186
	v_exp_f32_e32 v187, v187
	v_pk_mul_f32 v[190:191], v[104:105], v[150:151] op_sel_hi:[1,0]
	v_add_f32_e32 v186, 1.0, v186
	v_add_f32_e32 v187, 1.0, v187
	v_rcp_f32_e32 v186, v186
	v_rcp_f32_e32 v187, v187
	v_pk_mul_f32 v[150:151], v[102:103], v[150:151] op_sel_hi:[1,0]
	v_pk_mul_f32 v[152:153], v[152:153], v[186:187]
	s_nop 0
	v_pk_mul_f32 v[150:151], v[150:151], v[152:153]
	s_waitcnt lgkmcnt(0)
	v_pk_fma_f32 v[152:153], v[132:133], v[184:185], v[144:145]
	v_mul_lo_u32 v187, v192, s90
	v_pk_fma_f32 v[152:153], v[136:137], v[188:189], v[152:153]
	v_cvt_pk_bf16_f32 v150, v150, v151
	v_pk_fma_f32 v[152:153], v[140:141], v[146:147], v[152:153]
	v_add_u32_e32 v220, 0xb000, v187
	v_mul_f32_e32 v184, 0xbfb8aa3b, v152
	v_mul_f32_e32 v185, 0xbfb8aa3b, v153
	v_exp_f32_e32 v184, v184
	v_exp_f32_e32 v185, v185
	v_add_u32_e32 v230, 0x16000, v187
	v_add_f32_e32 v184, 1.0, v184
	v_add_f32_e32 v185, 1.0, v185
	v_rcp_f32_e32 v184, v184
	v_rcp_f32_e32 v185, v185
	s_nop 0
	v_pk_mul_f32 v[152:153], v[152:153], v[184:185]
	s_nop 0
	v_pk_mul_f32 v[152:153], v[190:191], v[152:153]
	v_lshl_or_b32 v184, v194, 3, v229
	v_cvt_pk_bf16_f32 v151, v152, v153
	v_add_lshl_u32 v152, v187, v176, 1
	global_store_dwordx2 v152, v[150:151], s[46:47]
	v_mov_b32_e32 v150, v238
	v_pk_mul_f32 v[190:191], v[92:93], v[150:151] op_sel_hi:[1,0]
	v_pk_mul_f32 v[188:189], v[94:95], v[150:151] op_sel_hi:[1,0]
	v_mov_b32_dpp v152, v148 row_ror:1 row_mask:0xf bank_mask:0xf
	v_mov_b32_dpp v152, v190 row_shr:1 row_mask:0xf bank_mask:0xf
	v_mov_b32_dpp v148, v148 row_ror:2 row_mask:0xf bank_mask:0xf
	v_mov_b32_dpp v148, v190 row_shr:2 row_mask:0xf bank_mask:0xf
	v_mov_b32_dpp v153, v149 row_ror:1 row_mask:0xf bank_mask:0xf
	v_mov_b32_dpp v153, v191 row_shr:1 row_mask:0xf bank_mask:0xf
	v_mov_b32_dpp v192, v146 row_ror:1 row_mask:0xf bank_mask:0xf
	v_mov_b32_dpp v192, v188 row_shr:1 row_mask:0xf bank_mask:0xf
	v_mov_b32_dpp v146, v146 row_ror:2 row_mask:0xf bank_mask:0xf
	v_mov_b32_dpp v146, v188 row_shr:2 row_mask:0xf bank_mask:0xf
	v_mov_b32_dpp v149, v149 row_ror:2 row_mask:0xf bank_mask:0xf
	v_mov_b32_dpp v149, v191 row_shr:2 row_mask:0xf bank_mask:0xf
	s_waitcnt lgkmcnt(2)
	v_pk_fma_f32 v[148:149], v[130:131], v[148:149], v[142:143]
	v_mov_b32_dpp v193, v147 row_ror:1 row_mask:0xf bank_mask:0xf
	v_mov_b32_dpp v193, v189 row_shr:1 row_mask:0xf bank_mask:0xf
	s_waitcnt lgkmcnt(1)
	v_pk_fma_f32 v[148:149], v[134:135], v[152:153], v[148:149]
	v_mov_b32_dpp v147, v147 row_ror:2 row_mask:0xf bank_mask:0xf
	v_mov_b32_dpp v147, v189 row_shr:2 row_mask:0xf bank_mask:0xf
	v_pk_fma_f32 v[148:149], v[138:139], v[190:191], v[148:149]
	v_mul_f32_e32 v152, 0xbfb8aa3b, v148
	v_mul_f32_e32 v153, 0xbfb8aa3b, v149
	v_exp_f32_e32 v152, v152
	v_exp_f32_e32 v153, v153
	v_add_f32_e32 v152, 1.0, v152
	v_add_f32_e32 v153, 1.0, v153
	v_rcp_f32_e32 v152, v152
	v_rcp_f32_e32 v153, v153
	s_waitcnt lgkmcnt(1)
	v_pk_fma_f32 v[146:147], v[132:133], v[146:147], v[144:145]
	v_pk_mul_f32 v[196:197], v[86:87], v[150:151] op_sel_hi:[1,0]
	s_waitcnt lgkmcnt(0)
; DI unsigned pk2(float lo, float hi) { f32x2 v = {lo, hi}; bf16x2_t b = __builtin_convertvector(v, bf16x2_t); return __builtin_bit_cast(unsigned, b); }
; DI float silu_f(float x) { return x * __builtin_amdgcn_rcpf(1.f + __builtin_amdgcn_exp2f(-LOG2E * x)); }
; DI float rstd_of(float ssq, float inv_n) { return 1.0f / sqrtf(ssq * inv_n + EPS); }
; DI float acc_get_i(const acc_t* base, unsigned idx, float inv_scale) { return (float)(*(const acc_t*)((const char*)base + idx * 8u)) * inv_scale; }
; template <class T> DI T* boff(T* base, unsigned byte_off) { return (T*)((char*)base + byte_off); }
;     DI void operator()(const f32x4 (&acc)[2][2][4][2], const Unit& u, int wr, int wc, int fr, int fq) const {
;     ...
;                 for (int m = 0; m < 4; ++m) { const int row = u.pm * BM + ai * HALF + wr * 64 + m * 16 + fr;
;                     const float rs = rstd_of(acc_get_i(ssq, (unsigned)row, 1.0f / SSQ_SCALE), 1.0f / DM);
;                     const f32x4 g = acc[ai][0][m][n] * rs, up = acc[ai][1][m][n] * rs;
;                     f32x4 a;
; #pragma unroll
;                     for (int j = 0; j < 4; ++j) { const float s1 = __shfl(fr == 15 ? pg[j] : g[j], src1), s2 = __shfl(fr >= 14 ? pg[j] : g[j], src2);
;                         a[j] = silu_f(cbv[j] + w0[j] * s2 + w1[j] * s1 + w2[j] * g[j]) * up[j]; }
;                     u32x2 gw; gw.x = pk2(g[0], g[1]); gw.y = pk2(g[2], g[3]);
;                     if (m == 0 && fr < 2) {
;                         *boff((u32x2*)GS, (unsigned)(((row >> 6) * 4 + 2 + fr) * DFF + c4) * 2u) = gw;
;                         u32x2 uw; uw.x = pk2(up[0], up[1]); uw.y = pk2(up[2], up[3]); *boff((u32x2*)US, (unsigned)(((row >> 6) * 2 + fr) * DFF + c4) * 2u) = uw;
;                     } else { u32x2 w; w.x = pk2(a[0], a[1]); w.y = pk2(a[2], a[3]); *boff((u32x2*)A2, (unsigned)(row * DFF + c4) * 2u) = w; }
;                     if (m == 3 && fr >= 14) {
;                         *boff((u32x2*)GS, (unsigned)(((row >> 6) * 4 + (fr - 14)) * DFF + c4) * 2u) = gw;
;                         if ((row & (SEQ - 1)) >= SEQ - 2) *boff((f32x4*)fcp, (unsigned)(((row >> 11) * 2 + ((row & (SEQ - 1)) - (SEQ - 2))) * DFF + c4) * 4u) = g;
;                     }
	v_pk_fma_f32 v[146:147], v[136:137], v[192:193], v[146:147]
	v_pk_mul_f32 v[150:151], v[84:85], v[150:151] op_sel_hi:[1,0]
	v_pk_mul_f32 v[148:149], v[148:149], v[152:153]
	v_pk_fma_f32 v[146:147], v[140:141], v[188:189], v[146:147]
	v_pk_mul_f32 v[148:149], v[150:151], v[148:149]
	v_mul_f32_e32 v150, 0xbfb8aa3b, v146
	v_mul_f32_e32 v151, 0xbfb8aa3b, v147
	v_exp_f32_e32 v150, v150
	v_exp_f32_e32 v151, v151
	v_cvt_pk_bf16_f32 v148, v148, v149
	v_or_b32_e32 v185, 48, v194
	v_add_f32_e32 v150, 1.0, v150
	v_add_f32_e32 v151, 1.0, v151
	v_rcp_f32_e32 v150, v150
	v_rcp_f32_e32 v151, v151
	v_lshlrev_b32_e32 v186, 3, v185
	v_pk_mul_f32 v[146:147], v[146:147], v[150:151]
	s_nop 0
	v_pk_mul_f32 v[146:147], v[196:197], v[146:147]
	s_nop 0
	v_cvt_pk_bf16_f32 v149, v146, v147
	v_add_lshl_u32 v146, v220, v176, 1
	global_store_dwordx2 v146, v[148:149], s[46:47]
	v_mov_b32_e32 v150, v239
	v_pk_mul_f32 v[146:147], v[76:77], v[150:151] op_sel_hi:[1,0]
	v_pk_mul_f32 v[148:149], v[78:79], v[150:151] op_sel_hi:[1,0]
	v_mov_b32_dpp v152, v190 row_ror:1 row_mask:0xf bank_mask:0xf
	v_mov_b32_dpp v152, v146 row_shr:1 row_mask:0xf bank_mask:0xf
	v_mov_b32_dpp v190, v190 row_ror:2 row_mask:0xf bank_mask:0xf
	v_mov_b32_dpp v190, v146 row_shr:2 row_mask:0xf bank_mask:0xf
	v_mov_b32_dpp v153, v191 row_ror:1 row_mask:0xf bank_mask:0xf
	v_mov_b32_dpp v153, v147 row_shr:1 row_mask:0xf bank_mask:0xf
	v_mov_b32_dpp v191, v191 row_ror:2 row_mask:0xf bank_mask:0xf
	v_mov_b32_dpp v191, v147 row_shr:2 row_mask:0xf bank_mask:0xf
	v_mov_b32_dpp v192, v188 row_ror:1 row_mask:0xf bank_mask:0xf
	v_mov_b32_dpp v192, v148 row_shr:1 row_mask:0xf bank_mask:0xf
	v_mov_b32_dpp v188, v188 row_ror:2 row_mask:0xf bank_mask:0xf
	v_mov_b32_dpp v188, v148 row_shr:2 row_mask:0xf bank_mask:0xf
	s_waitcnt lgkmcnt(2)
	v_pk_fma_f32 v[190:191], v[130:131], v[190:191], v[142:143]
	v_mov_b32_dpp v193, v189 row_ror:1 row_mask:0xf bank_mask:0xf
	v_mov_b32_dpp v193, v149 row_shr:1 row_mask:0xf bank_mask:0xf
	v_pk_fma_f32 v[152:153], v[134:135], v[152:153], v[190:191]
	v_pk_fma_f32 v[152:153], v[138:139], v[146:147], v[152:153]
	v_mov_b32_dpp v189, v189 row_ror:2 row_mask:0xf bank_mask:0xf
	v_mov_b32_dpp v189, v149 row_shr:2 row_mask:0xf bank_mask:0xf
	v_mul_f32_e32 v190, 0xbfb8aa3b, v152
	v_mul_f32_e32 v191, 0xbfb8aa3b, v153
	v_exp_f32_e32 v190, v190
	v_exp_f32_e32 v191, v191
	v_pk_mul_f32 v[194:195], v[70:71], v[150:151] op_sel_hi:[1,0]
	v_add_f32_e32 v190, 1.0, v190
	v_add_f32_e32 v191, 1.0, v191
	v_rcp_f32_e32 v190, v190
	v_rcp_f32_e32 v191, v191
	v_pk_mul_f32 v[150:151], v[68:69], v[150:151] op_sel_hi:[1,0]
	v_pk_mul_f32 v[152:153], v[152:153], v[190:191]
	s_nop 0
	v_pk_mul_f32 v[150:151], v[150:151], v[152:153]
	s_waitcnt lgkmcnt(0)
	v_pk_fma_f32 v[152:153], v[132:133], v[188:189], v[144:145]
	s_nop 0
	v_pk_fma_f32 v[152:153], v[136:137], v[192:193], v[152:153]
	s_nop 0
	v_pk_fma_f32 v[152:153], v[140:141], v[148:149], v[152:153]
	s_nop 0
	v_mul_f32_e32 v188, 0xbfb8aa3b, v152
	v_mul_f32_e32 v189, 0xbfb8aa3b, v153
	v_exp_f32_e32 v188, v188
	v_exp_f32_e32 v189, v189
	v_add_f32_e32 v188, 1.0, v188
	v_add_f32_e32 v189, 1.0, v189
	v_rcp_f32_e32 v188, v188
	v_rcp_f32_e32 v189, v189
	s_nop 0
	v_pk_mul_f32 v[152:153], v[152:153], v[188:189]
	s_nop 0
	v_pk_mul_f32 v[152:153], v[194:195], v[152:153]
	v_cvt_pk_bf16_f32 v188, v150, v151
	v_cvt_pk_bf16_f32 v189, v152, v153
	v_add_lshl_u32 v150, v230, v176, 1
	global_store_dwordx2 v150, v[188:189], s[46:47]
	v_and_b32_e32 v189, 0x7ff, v185
	s_and_saveexec_b64 s[0:1], s[38:39]
	s_cbranch_execz .LBB0_3100
	s_movk_i32 s2, 0x7fd
	v_add_lshl_u32 v152, v217, v176, 1
	v_cvt_pk_bf16_f32 v150, v146, v147
	v_cvt_pk_bf16_f32 v151, v148, v149
	v_cmp_lt_u32_e32 vcc, s2, v189
	global_store_dwordx2 v152, v[150:151], s[50:51]
	s_and_b64 exec, exec, vcc
	s_cbranch_execz .LBB0_3100
	v_add_u32_e32 v150, s14, v189
	v_mul_lo_u32 v150, v150, s90
	v_add_lshl_u32 v150, v150, v176, 2
	global_store_dwordx4 v150, v[146:149], s[58:59]
.LBB0_3100:
	s_or_b64 exec, exec, s[0:1]
	s_addk_i32 s15, 0x80
	v_or_b32_e32 v185, s15, v209
	v_lshlrev_b32_e32 v188, 3, v185
	v_mul_lo_u32 v231, v185, s90
	v_mov_b32_e32 v148, v240
	v_pk_mul_f32 v[194:195], v[60:61], v[148:149] op_sel_hi:[1,0]
	v_pk_mul_f32 v[192:193], v[62:63], v[148:149] op_sel_hi:[1,0]
	v_mov_b32_e32 v190, 0
	v_mov_b32_dpp v190, v194 row_shr:1 row_mask:0xf bank_mask:0xf
	v_mov_b32_e32 v198, 0
	v_mov_b32_dpp v198, v194 row_shr:2 row_mask:0xf bank_mask:0xf
	v_mov_b32_e32 v191, 0
	v_mov_b32_dpp v191, v195 row_shr:1 row_mask:0xf bank_mask:0xf
	v_mov_b32_e32 v199, 0
	v_mov_b32_dpp v199, v195 row_shr:2 row_mask:0xf bank_mask:0xf
	v_mov_b32_e32 v196, 0
	v_mov_b32_dpp v196, v192 row_shr:1 row_mask:0xf bank_mask:0xf
	v_mov_b32_e32 v200, 0
	v_mov_b32_dpp v200, v192 row_shr:2 row_mask:0xf bank_mask:0xf
	v_mov_b32_e32 v197, 0
	v_mov_b32_dpp v197, v193 row_shr:1 row_mask:0xf bank_mask:0xf
	v_mov_b32_e32 v201, 0
	v_mov_b32_dpp v201, v193 row_shr:2 row_mask:0xf bank_mask:0xf
	v_pk_mul_f32 v[146:147], v[54:55], v[148:149] op_sel_hi:[1,0]
	v_pk_mul_f32 v[148:149], v[52:53], v[148:149] op_sel_hi:[1,0]
	s_and_saveexec_b64 s[0:1], s[40:41]
	s_xor_b64 s[0:1], exec, s[0:1]
	s_cbranch_execz .LBB0_3102
	s_waitcnt lgkmcnt(4)
	v_pk_fma_f32 v[150:151], v[130:131], v[198:199], v[142:143]
	s_nop 0
	v_pk_fma_f32 v[150:151], v[134:135], v[190:191], v[150:151]
	s_waitcnt lgkmcnt(0)
	v_pk_fma_f32 v[190:191], v[132:133], v[200:201], v[144:145]
	v_pk_fma_f32 v[150:151], v[138:139], v[194:195], v[150:151]
	v_pk_fma_f32 v[190:191], v[136:137], v[196:197], v[190:191]
	v_mul_f32_e32 v152, 0xbfb8aa3b, v150
	v_mul_f32_e32 v153, 0xbfb8aa3b, v151
	v_pk_fma_f32 v[190:191], v[140:141], v[192:193], v[190:191]
	v_exp_f32_e32 v152, v152
	v_exp_f32_e32 v153, v153
	v_mul_f32_e32 v196, 0xbfb8aa3b, v190
	v_mul_f32_e32 v197, 0xbfb8aa3b, v191
	v_exp_f32_e32 v196, v196
	v_exp_f32_e32 v197, v197
	v_add_f32_e32 v152, 1.0, v152
	v_add_f32_e32 v153, 1.0, v153
	v_rcp_f32_e32 v152, v152
	v_rcp_f32_e32 v153, v153
	v_add_f32_e32 v196, 1.0, v196
	v_add_f32_e32 v197, 1.0, v197
	v_rcp_f32_e32 v196, v196
	v_rcp_f32_e32 v197, v197
	v_pk_mul_f32 v[150:151], v[150:151], v[152:153]
	s_nop 0
	v_pk_mul_f32 v[148:149], v[148:149], v[150:151]
	v_pk_mul_f32 v[150:151], v[190:191], v[196:197]
	v_cvt_pk_bf16_f32 v148, v148, v149
	v_pk_mul_f32 v[146:147], v[146:147], v[150:151]
	s_nop 0
	v_cvt_pk_bf16_f32 v149, v146, v147
	v_add_lshl_u32 v146, v231, v176, 1
	global_store_dwordx2 v146, v[148:149], s[46:47]

; DI unsigned pk2(float lo, float hi) { f32x2 v = {lo, hi}; bf16x2_t b = __builtin_convertvector(v, bf16x2_t); return __builtin_bit_cast(unsigned, b); }
; DI float silu_f(float x) { return x * __builtin_amdgcn_rcpf(1.f + __builtin_amdgcn_exp2f(-LOG2E * x)); }
; DI float rstd_of(float ssq, float inv_n) { return 1.0f / sqrtf(ssq * inv_n + EPS); }
; DI float acc_get_i(const acc_t* base, unsigned idx, float inv_scale) { return (float)(*(const acc_t*)((const char*)base + idx * 8u)) * inv_scale; }
; template <class T> DI T* boff(T* base, unsigned byte_off) { return (T*)((char*)base + byte_off); }
;     DI void operator()(const f32x4 (&acc)[2][2][4][2], const Unit& u, int wr, int wc, int fr, int fq) const {
;     ...
;                 for (int m = 0; m < 4; ++m) { const int row = u.pm * BM + ai * HALF + wr * 64 + m * 16 + fr;
;                     const float rs = rstd_of(acc_get_i(ssq, (unsigned)row, 1.0f / SSQ_SCALE), 1.0f / DM);
;                     const f32x4 g = acc[ai][0][m][n] * rs, up = acc[ai][1][m][n] * rs;
;                     f32x4 a;
; #pragma unroll
;                     for (int j = 0; j < 4; ++j) { const float s1 = __shfl(fr == 15 ? pg[j] : g[j], src1), s2 = __shfl(fr >= 14 ? pg[j] : g[j], src2);
;                         a[j] = silu_f(cbv[j] + w0[j] * s2 + w1[j] * s1 + w2[j] * g[j]) * up[j]; }
;                     u32x2 gw; gw.x = pk2(g[0], g[1]); gw.y = pk2(g[2], g[3]);
;                     if (m == 0 && fr < 2) {
;                         *boff((u32x2*)GS, (unsigned)(((row >> 6) * 4 + 2 + fr) * DFF + c4) * 2u) = gw;
;                         u32x2 uw; uw.x = pk2(up[0], up[1]); uw.y = pk2(up[2], up[3]); *boff((u32x2*)US, (unsigned)(((row >> 6) * 2 + fr) * DFF + c4) * 2u) = uw;
;                     } else { u32x2 w; w.x = pk2(a[0], a[1]); w.y = pk2(a[2], a[3]); *boff((u32x2*)A2, (unsigned)(row * DFF + c4) * 2u) = w; }
;                     if (m == 3 && fr >= 14) {
;                         *boff((u32x2*)GS, (unsigned)(((row >> 6) * 4 + (fr - 14)) * DFF + c4) * 2u) = gw;
;                         if ((row & (SEQ - 1)) >= SEQ - 2) *boff((f32x4*)fcp, (unsigned)(((row >> 11) * 2 + ((row & (SEQ - 1)) - (SEQ - 2))) * DFF + c4) * 4u) = g;
;                     }
.LBB0_3104:
	s_or_b64 exec, exec, s[0:1]
	s_waitcnt lgkmcnt(2)
	v_or_b32_e32 v200, 16, v185
	v_add_u32_e32 v146, s2, v212
	v_lshlrev_b32_e32 v190, 3, v200
	v_mul_lo_u32 v221, v146, s90
	s_ashr_i32 s0, s15, 10
	s_and_b32 s15, s0, 0x3ffffffe
	s_add_i32 s15, s15, 0x3ffff802
	v_mov_b32_e32 v150, v241
	v_pk_mul_f32 v[148:149], v[44:45], v[150:151] op_sel_hi:[1,0]
	v_pk_mul_f32 v[146:147], v[46:47], v[150:151] op_sel_hi:[1,0]
	v_mov_b32_dpp v152, v194 row_ror:1 row_mask:0xf bank_mask:0xf
	v_mov_b32_dpp v152, v148 row_shr:1 row_mask:0xf bank_mask:0xf
	v_mov_b32_dpp v194, v194 row_ror:2 row_mask:0xf bank_mask:0xf
	v_mov_b32_dpp v194, v148 row_shr:2 row_mask:0xf bank_mask:0xf
	v_mov_b32_dpp v153, v195 row_ror:1 row_mask:0xf bank_mask:0xf
	v_mov_b32_dpp v153, v149 row_shr:1 row_mask:0xf bank_mask:0xf
	v_mov_b32_dpp v195, v195 row_ror:2 row_mask:0xf bank_mask:0xf
	v_mov_b32_dpp v195, v149 row_shr:2 row_mask:0xf bank_mask:0xf
	v_mov_b32_dpp v196, v192 row_ror:1 row_mask:0xf bank_mask:0xf
	v_mov_b32_dpp v196, v146 row_shr:1 row_mask:0xf bank_mask:0xf
	v_mov_b32_dpp v192, v192 row_ror:2 row_mask:0xf bank_mask:0xf
	v_mov_b32_dpp v192, v146 row_shr:2 row_mask:0xf bank_mask:0xf
	s_waitcnt lgkmcnt(2)
	v_pk_fma_f32 v[194:195], v[130:131], v[194:195], v[142:143]
	v_mov_b32_dpp v197, v193 row_ror:1 row_mask:0xf bank_mask:0xf
	v_mov_b32_dpp v197, v147 row_shr:1 row_mask:0xf bank_mask:0xf
	v_pk_fma_f32 v[152:153], v[134:135], v[152:153], v[194:195]
	v_pk_fma_f32 v[152:153], v[138:139], v[148:149], v[152:153]
	v_mov_b32_dpp v193, v193 row_ror:2 row_mask:0xf bank_mask:0xf
	v_mov_b32_dpp v193, v147 row_shr:2 row_mask:0xf bank_mask:0xf
	v_mul_f32_e32 v194, 0xbfb8aa3b, v152
	v_mul_f32_e32 v195, 0xbfb8aa3b, v153
	v_exp_f32_e32 v194, v194
	v_exp_f32_e32 v195, v195
	v_pk_mul_f32 v[198:199], v[38:39], v[150:151] op_sel_hi:[1,0]
	v_add_f32_e32 v194, 1.0, v194
	v_add_f32_e32 v195, 1.0, v195
	v_rcp_f32_e32 v194, v194
	v_rcp_f32_e32 v195, v195
	v_pk_mul_f32 v[150:151], v[36:37], v[150:151] op_sel_hi:[1,0]
	v_pk_mul_f32 v[152:153], v[152:153], v[194:195]
	s_nop 0
	v_pk_mul_f32 v[150:151], v[150:151], v[152:153]
	s_waitcnt lgkmcnt(0)
	v_pk_fma_f32 v[152:153], v[132:133], v[192:193], v[144:145]
	v_mul_lo_u32 v195, v200, s90
	v_pk_fma_f32 v[152:153], v[136:137], v[196:197], v[152:153]
	v_cvt_pk_bf16_f32 v150, v150, v151
	v_pk_fma_f32 v[152:153], v[140:141], v[146:147], v[152:153]
	v_add_u32_e32 v233, 0xb000, v195
	v_mul_f32_e32 v192, 0xbfb8aa3b, v152
	v_mul_f32_e32 v193, 0xbfb8aa3b, v153
	v_exp_f32_e32 v192, v192
	v_exp_f32_e32 v193, v193
	v_add_u32_e32 v234, 0x16000, v195
	v_add_f32_e32 v192, 1.0, v192
	v_add_f32_e32 v193, 1.0, v193
	v_rcp_f32_e32 v192, v192
	v_rcp_f32_e32 v193, v193
	s_nop 0
	v_pk_mul_f32 v[152:153], v[152:153], v[192:193]
	s_nop 0
	v_pk_mul_f32 v[152:153], v[198:199], v[152:153]
	v_lshl_or_b32 v192, v185, 3, v229
	v_cvt_pk_bf16_f32 v151, v152, v153
	v_add_lshl_u32 v152, v195, v176, 1
	global_store_dwordx2 v152, v[150:151], s[46:47]
	v_or_b32_e32 v185, 48, v185
	v_and_b32_e32 v235, 0x7ff, v185
	v_mov_b32_e32 v150, v242
	v_pk_mul_f32 v[198:199], v[28:29], v[150:151] op_sel_hi:[1,0]
	v_pk_mul_f32 v[196:197], v[30:31], v[150:151] op_sel_hi:[1,0]
	v_mov_b32_dpp v152, v148 row_ror:1 row_mask:0xf bank_mask:0xf
	v_mov_b32_dpp v152, v198 row_shr:1 row_mask:0xf bank_mask:0xf
	v_mov_b32_dpp v148, v148 row_ror:2 row_mask:0xf bank_mask:0xf
	v_mov_b32_dpp v148, v198 row_shr:2 row_mask:0xf bank_mask:0xf
	v_mov_b32_dpp v153, v149 row_ror:1 row_mask:0xf bank_mask:0xf
	v_mov_b32_dpp v153, v199 row_shr:1 row_mask:0xf bank_mask:0xf
	v_mov_b32_dpp v200, v146 row_ror:1 row_mask:0xf bank_mask:0xf
	v_mov_b32_dpp v200, v196 row_shr:1 row_mask:0xf bank_mask:0xf
	v_mov_b32_dpp v146, v146 row_ror:2 row_mask:0xf bank_mask:0xf
	v_mov_b32_dpp v146, v196 row_shr:2 row_mask:0xf bank_mask:0xf
	v_mov_b32_dpp v149, v149 row_ror:2 row_mask:0xf bank_mask:0xf
	v_mov_b32_dpp v149, v199 row_shr:2 row_mask:0xf bank_mask:0xf
	s_waitcnt lgkmcnt(2)
	v_pk_fma_f32 v[148:149], v[130:131], v[148:149], v[142:143]
	v_mov_b32_dpp v201, v147 row_ror:1 row_mask:0xf bank_mask:0xf
	v_mov_b32_dpp v201, v197 row_shr:1 row_mask:0xf bank_mask:0xf
	s_waitcnt lgkmcnt(1)
	v_pk_fma_f32 v[148:149], v[134:135], v[152:153], v[148:149]
	v_mov_b32_dpp v147, v147 row_ror:2 row_mask:0xf bank_mask:0xf
	v_mov_b32_dpp v147, v197 row_shr:2 row_mask:0xf bank_mask:0xf
	v_pk_fma_f32 v[148:149], v[138:139], v[198:199], v[148:149]
	v_mul_f32_e32 v152, 0xbfb8aa3b, v148
	v_mul_f32_e32 v153, 0xbfb8aa3b, v149
	v_exp_f32_e32 v152, v152
	v_exp_f32_e32 v153, v153
	v_add_f32_e32 v152, 1.0, v152
	v_add_f32_e32 v153, 1.0, v153
	v_rcp_f32_e32 v152, v152
	v_rcp_f32_e32 v153, v153
	s_waitcnt lgkmcnt(1)
	v_pk_fma_f32 v[146:147], v[132:133], v[146:147], v[144:145]
	v_pk_mul_f32 v[202:203], v[22:23], v[150:151] op_sel_hi:[1,0]
	s_waitcnt lgkmcnt(0)
; DI unsigned pk2(float lo, float hi) { f32x2 v = {lo, hi}; bf16x2_t b = __builtin_convertvector(v, bf16x2_t); return __builtin_bit_cast(unsigned, b); }
; DI float silu_f(float x) { return x * __builtin_amdgcn_rcpf(1.f + __builtin_amdgcn_exp2f(-LOG2E * x)); }
; DI float rstd_of(float ssq, float inv_n) { return 1.0f / sqrtf(ssq * inv_n + EPS); }
; template <class T> DI T* boff(T* base, unsigned byte_off) { return (T*)((char*)base + byte_off); }
;     DI void operator()(const f32x4 (&acc)[2][2][4][2], const Unit& u, int wr, int wc, int fr, int fq) const {
;     ...
;             const int c4 = c8 + 4 * n;
;             const f32x4 w0 = *(const f32x4*)(cw + c4), w1 = *(const f32x4*)(cw + DFF + c4), w2 = *(const f32x4*)(cw + 2 * DFF + c4), cbv = *(const f32x4*)(cb + c4);
; #pragma unroll
;             for (int ai = 0; ai < 2; ++ai) {
;                 f32x4 pg = {0.f, 0.f, 0.f, 0.f};
; #pragma unroll
;                 for (int m = 0; m < 4; ++m) { const int row = u.pm * BM + ai * HALF + wr * 64 + m * 16 + fr;
;                     const float rs = rstd_of(acc_get_i(ssq, (unsigned)row, 1.0f / SSQ_SCALE), 1.0f / DM);
;                     const f32x4 g = acc[ai][0][m][n] * rs, up = acc[ai][1][m][n] * rs;
;                     f32x4 a;
; #pragma unroll
;                     for (int j = 0; j < 4; ++j) { const float s1 = __shfl(fr == 15 ? pg[j] : g[j], src1), s2 = __shfl(fr >= 14 ? pg[j] : g[j], src2);
;                         a[j] = silu_f(cbv[j] + w0[j] * s2 + w1[j] * s1 + w2[j] * g[j]) * up[j]; }
;                     u32x2 gw; gw.x = pk2(g[0], g[1]); gw.y = pk2(g[2], g[3]);
;                     if (m == 0 && fr < 2) {
;                         *boff((u32x2*)GS, (unsigned)(((row >> 6) * 4 + 2 + fr) * DFF + c4) * 2u) = gw;
;                         u32x2 uw; uw.x = pk2(up[0], up[1]); uw.y = pk2(up[2], up[3]); *boff((u32x2*)US, (unsigned)(((row >> 6) * 2 + fr) * DFF + c4) * 2u) = uw;
;                     } else { u32x2 w; w.x = pk2(a[0], a[1]); w.y = pk2(a[2], a[3]); *boff((u32x2*)A2, (unsigned)(row * DFF + c4) * 2u) = w; }
;                     if (m == 3 && fr >= 14) {
;                         *boff((u32x2*)GS, (unsigned)(((row >> 6) * 4 + (fr - 14)) * DFF + c4) * 2u) = gw;
;                         if ((row & (SEQ - 1)) >= SEQ - 2) *boff((f32x4*)fcp, (unsigned)(((row >> 11) * 2 + ((row & (SEQ - 1)) - (SEQ - 2))) * DFF + c4) * 4u) = g;
;                     }
	v_pk_fma_f32 v[146:147], v[136:137], v[200:201], v[146:147]
	v_pk_mul_f32 v[150:151], v[20:21], v[150:151] op_sel_hi:[1,0]
	v_pk_mul_f32 v[148:149], v[148:149], v[152:153]
	v_pk_fma_f32 v[146:147], v[140:141], v[196:197], v[146:147]
	v_pk_mul_f32 v[148:149], v[150:151], v[148:149]
	v_mul_f32_e32 v150, 0xbfb8aa3b, v146
	v_mul_f32_e32 v151, 0xbfb8aa3b, v147
	v_exp_f32_e32 v150, v150
	v_exp_f32_e32 v151, v151
	v_cvt_pk_bf16_f32 v148, v148, v149
	v_lshlrev_b32_e32 v194, 3, v185
	v_add_f32_e32 v150, 1.0, v150
	v_add_f32_e32 v151, 1.0, v151
	v_rcp_f32_e32 v150, v150
	v_rcp_f32_e32 v151, v151
	s_nop 0
	v_pk_mul_f32 v[146:147], v[146:147], v[150:151]
	s_nop 0
	v_pk_mul_f32 v[146:147], v[202:203], v[146:147]
	s_nop 0
	v_cvt_pk_bf16_f32 v149, v146, v147
	v_add_lshl_u32 v146, v233, v176, 1
	global_store_dwordx2 v146, v[148:149], s[46:47]
	v_mov_b32_e32 v150, v243
	v_pk_mul_f32 v[146:147], v[12:13], v[150:151] op_sel_hi:[1,0]
	v_pk_mul_f32 v[148:149], v[14:15], v[150:151] op_sel_hi:[1,0]
	v_mov_b32_dpp v152, v198 row_ror:1 row_mask:0xf bank_mask:0xf
	v_mov_b32_dpp v152, v146 row_shr:1 row_mask:0xf bank_mask:0xf
	v_mov_b32_dpp v198, v198 row_ror:2 row_mask:0xf bank_mask:0xf
	v_mov_b32_dpp v198, v146 row_shr:2 row_mask:0xf bank_mask:0xf
	v_mov_b32_dpp v153, v199 row_ror:1 row_mask:0xf bank_mask:0xf
	v_mov_b32_dpp v153, v147 row_shr:1 row_mask:0xf bank_mask:0xf
	v_mov_b32_dpp v199, v199 row_ror:2 row_mask:0xf bank_mask:0xf
	v_mov_b32_dpp v199, v147 row_shr:2 row_mask:0xf bank_mask:0xf
	v_mov_b32_dpp v200, v196 row_ror:1 row_mask:0xf bank_mask:0xf
	v_mov_b32_dpp v200, v148 row_shr:1 row_mask:0xf bank_mask:0xf
	v_mov_b32_dpp v196, v196 row_ror:2 row_mask:0xf bank_mask:0xf
	v_mov_b32_dpp v196, v148 row_shr:2 row_mask:0xf bank_mask:0xf
	s_waitcnt lgkmcnt(2)
	v_pk_fma_f32 v[130:131], v[130:131], v[198:199], v[142:143]
	v_mov_b32_dpp v201, v197 row_ror:1 row_mask:0xf bank_mask:0xf
	v_mov_b32_dpp v201, v149 row_shr:1 row_mask:0xf bank_mask:0xf
	v_pk_fma_f32 v[130:131], v[134:135], v[152:153], v[130:131]
	v_pk_fma_f32 v[130:131], v[138:139], v[146:147], v[130:131]
	v_mov_b32_dpp v197, v197 row_ror:2 row_mask:0xf bank_mask:0xf
	v_mov_b32_dpp v197, v149 row_shr:2 row_mask:0xf bank_mask:0xf
	v_mul_f32_e32 v134, 0xbfb8aa3b, v130
	v_mul_f32_e32 v135, 0xbfb8aa3b, v131
	v_exp_f32_e32 v134, v134
	v_exp_f32_e32 v135, v135
	v_pk_mul_f32 v[202:203], v[6:7], v[150:151] op_sel_hi:[1,0]
	v_add_f32_e32 v134, 1.0, v134
	v_add_f32_e32 v135, 1.0, v135
	v_rcp_f32_e32 v134, v134
	v_rcp_f32_e32 v135, v135
	s_waitcnt lgkmcnt(0)
	v_pk_fma_f32 v[132:133], v[132:133], v[196:197], v[144:145]
	v_pk_mul_f32 v[150:151], v[4:5], v[150:151] op_sel_hi:[1,0]
	v_pk_fma_f32 v[132:133], v[136:137], v[200:201], v[132:133]
	v_pk_mul_f32 v[130:131], v[130:131], v[134:135]
	v_pk_fma_f32 v[132:133], v[140:141], v[148:149], v[132:133]
	v_pk_mul_f32 v[130:131], v[150:151], v[130:131]
	v_mul_f32_e32 v134, 0xbfb8aa3b, v132
	v_mul_f32_e32 v135, 0xbfb8aa3b, v133
	v_exp_f32_e32 v134, v134
	v_exp_f32_e32 v135, v135
	v_cvt_pk_bf16_f32 v130, v130, v131
	v_add_f32_e32 v134, 1.0, v134
	v_add_f32_e32 v135, 1.0, v135
	v_rcp_f32_e32 v134, v134
	v_rcp_f32_e32 v135, v135
	s_nop 0
	v_pk_mul_f32 v[132:133], v[132:133], v[134:135]
	s_nop 0
	v_pk_mul_f32 v[132:133], v[202:203], v[132:133]
	s_nop 0
	v_cvt_pk_bf16_f32 v131, v132, v133
	v_add_lshl_u32 v132, v234, v176, 1
	global_store_dwordx2 v132, v[130:131], s[46:47]
	s_and_saveexec_b64 s[0:1], s[38:39]
	s_cbranch_execz .LBB0_3107
	s_movk_i32 s2, 0x7fd
	v_add_lshl_u32 v132, v221, v176, 1
	v_cvt_pk_bf16_f32 v130, v146, v147
	v_cvt_pk_bf16_f32 v131, v148, v149
	v_cmp_lt_u32_e32 vcc, s2, v235
	global_store_dwordx2 v132, v[130:131], s[50:51]
	s_and_b64 exec, exec, vcc
	s_cbranch_execz .LBB0_3107
	v_add_u32_e32 v130, s15, v235
	v_mul_lo_u32 v130, v130, s90
	v_add_lshl_u32 v130, v130, v176, 2
	global_store_dwordx4 v130, v[146:149], s[58:59]
.LBB0_3107:
	s_or_b64 exec, exec, s[0:1]
	v_or_b32_e32 v196, 4, v176
	v_ashrrev_i32_e32 v197, 31, v196
	v_lshlrev_b64 v[134:135], 2, v[196:197]
	v_lshl_add_u64 v[146:147], s[48:49], 0, v[96:97]
	v_lshl_add_u64 v[136:137], s[62:63], 0, v[134:135]
	v_lshl_add_u64 v[134:135], s[64:65], 0, v[134:135]
	global_load_dwordx4 v[130:133], v[178:179], off offset:16
	global_load_dwordx4 v[138:141], v[136:137], off
	s_nop 0
	global_load_dwordx4 v[134:137], v[134:135], off
	s_nop 0
	global_load_dwordx4 v[142:145], v[180:181], off offset:16
	s_nop 0
	s_waitcnt vmcnt(0)
	v_mov_b32_e32 v96, v236
	v_pk_mul_f32 v[148:149], v[122:123], v[96:97] op_sel_hi:[1,0]
	v_pk_mul_f32 v[146:147], v[124:125], v[96:97] op_sel_hi:[1,0]
	v_pk_mul_f32 v[178:179], v[116:117], v[96:97] op_sel_hi:[1,0]
	v_pk_mul_f32 v[180:181], v[114:115], v[96:97] op_sel_hi:[1,0]
	v_mov_b32_e32 v200, 0
	v_mov_b32_dpp v200, v148 row_shr:1 row_mask:0xf bank_mask:0xf
	v_mov_b32_e32 v204, 0
	v_mov_b32_dpp v204, v148 row_shr:2 row_mask:0xf bank_mask:0xf
	v_mov_b32_e32 v201, 0
	v_mov_b32_dpp v201, v149 row_shr:1 row_mask:0xf bank_mask:0xf
	v_mov_b32_e32 v205, 0
	v_mov_b32_dpp v205, v149 row_shr:2 row_mask:0xf bank_mask:0xf
	v_mov_b32_e32 v198, 0
	v_mov_b32_dpp v198, v146 row_shr:1 row_mask:0xf bank_mask:0xf
	v_mov_b32_e32 v202, 0
	v_mov_b32_dpp v202, v146 row_shr:2 row_mask:0xf bank_mask:0xf
	v_mov_b32_e32 v199, 0
	v_mov_b32_dpp v199, v147 row_shr:1 row_mask:0xf bank_mask:0xf
	v_mov_b32_e32 v203, 0
	v_mov_b32_dpp v203, v147 row_shr:2 row_mask:0xf bank_mask:0xf
	s_and_saveexec_b64 s[0:1], s[40:41]
	s_xor_b64 s[0:1], exec, s[0:1]
	s_cbranch_execz .LBB0_3109
	s_waitcnt lgkmcnt(4)
	v_pk_fma_f32 v[150:151], v[130:131], v[204:205], v[142:143]
	s_nop 0
	v_pk_fma_f32 v[150:151], v[138:139], v[200:201], v[150:151]
	s_waitcnt lgkmcnt(0)
	v_pk_fma_f32 v[200:201], v[132:133], v[202:203], v[144:145]
	v_pk_fma_f32 v[150:151], v[134:135], v[148:149], v[150:151]
	v_pk_fma_f32 v[198:199], v[140:141], v[198:199], v[200:201]
	v_mul_f32_e32 v96, 0xbfb8aa3b, v150
	v_exp_f32_e32 v96, v96
	v_mul_f32_e32 v152, 0xbfb8aa3b, v151
	v_exp_f32_e32 v152, v152
	v_pk_fma_f32 v[198:199], v[136:137], v[146:147], v[198:199]
	v_add_f32_e32 v96, 1.0, v96
	v_mul_f32_e32 v183, 0xbfb8aa3b, v199
	v_add_f32_e32 v153, 1.0, v152
	v_rcp_f32_e32 v152, v96
	v_mul_f32_e32 v96, 0xbfb8aa3b, v198
	v_exp_f32_e32 v96, v96
	v_exp_f32_e32 v183, v183
	v_rcp_f32_e32 v153, v153
	v_add_f32_e32 v96, 1.0, v96
	v_rcp_f32_e32 v200, v96
	v_add_f32_e32 v96, 1.0, v183
	v_rcp_f32_e32 v201, v96
	v_pk_mul_f32 v[150:151], v[150:151], v[152:153]
	v_add_lshl_u32 v96, v218, v196, 1
	v_pk_mul_f32 v[150:151], v[180:181], v[150:151]
	v_pk_mul_f32 v[152:153], v[198:199], v[200:201]
	v_cvt_pk_bf16_f32 v150, v150, v151
	v_pk_mul_f32 v[152:153], v[178:179], v[152:153]
	s_nop 0
	v_cvt_pk_bf16_f32 v151, v152, v153
	global_store_dwordx2 v96, v[150:151], s[46:47]

; DI unsigned pk2(float lo, float hi) { f32x2 v = {lo, hi}; bf16x2_t b = __builtin_convertvector(v, bf16x2_t); return __builtin_bit_cast(unsigned, b); }
; DI float silu_f(float x) { return x * __builtin_amdgcn_rcpf(1.f + __builtin_amdgcn_exp2f(-LOG2E * x)); }
; DI float rstd_of(float ssq, float inv_n) { return 1.0f / sqrtf(ssq * inv_n + EPS); }
; DI float acc_get_i(const acc_t* base, unsigned idx, float inv_scale) { return (float)(*(const acc_t*)((const char*)base + idx * 8u)) * inv_scale; }
; template <class T> DI T* boff(T* base, unsigned byte_off) { return (T*)((char*)base + byte_off); }
;     DI void operator()(const f32x4 (&acc)[2][2][4][2], const Unit& u, int wr, int wc, int fr, int fq) const {
;     ...
;                 for (int m = 0; m < 4; ++m) { const int row = u.pm * BM + ai * HALF + wr * 64 + m * 16 + fr;
;                     const float rs = rstd_of(acc_get_i(ssq, (unsigned)row, 1.0f / SSQ_SCALE), 1.0f / DM);
;                     const f32x4 g = acc[ai][0][m][n] * rs, up = acc[ai][1][m][n] * rs;
;                     f32x4 a;
; #pragma unroll
;                     for (int j = 0; j < 4; ++j) { const float s1 = __shfl(fr == 15 ? pg[j] : g[j], src1), s2 = __shfl(fr >= 14 ? pg[j] : g[j], src2);
;                         a[j] = silu_f(cbv[j] + w0[j] * s2 + w1[j] * s1 + w2[j] * g[j]) * up[j]; }
;                     u32x2 gw; gw.x = pk2(g[0], g[1]); gw.y = pk2(g[2], g[3]);
;                     if (m == 0 && fr < 2) {
;                         *boff((u32x2*)GS, (unsigned)(((row >> 6) * 4 + 2 + fr) * DFF + c4) * 2u) = gw;
;                         u32x2 uw; uw.x = pk2(up[0], up[1]); uw.y = pk2(up[2], up[3]); *boff((u32x2*)US, (unsigned)(((row >> 6) * 2 + fr) * DFF + c4) * 2u) = uw;
;                     } else { u32x2 w; w.x = pk2(a[0], a[1]); w.y = pk2(a[2], a[3]); *boff((u32x2*)A2, (unsigned)(row * DFF + c4) * 2u) = w; }
;                     if (m == 3 && fr >= 14) {
;                         *boff((u32x2*)GS, (unsigned)(((row >> 6) * 4 + (fr - 14)) * DFF + c4) * 2u) = gw;
;                         if ((row & (SEQ - 1)) >= SEQ - 2) *boff((f32x4*)fcp, (unsigned)(((row >> 11) * 2 + ((row & (SEQ - 1)) - (SEQ - 2))) * DFF + c4) * 4u) = g;
;                     }
.LBB0_3111:
	s_or_b64 exec, exec, s[0:1]
	v_mov_b32_e32 v183, v97
	v_lshl_add_u64 v[150:151], s[48:49], 0, v[182:183]
	v_add_lshl_u32 v187, v187, v196, 1
	v_mov_b32_e32 v185, v97
	v_lshl_add_u64 v[184:185], s[48:49], 0, v[184:185]
	v_mov_b32_e32 v150, v237
	v_pk_mul_f32 v[152:153], v[108:109], v[150:151] op_sel_hi:[1,0]
	v_pk_mul_f32 v[178:179], v[106:107], v[150:151] op_sel_hi:[1,0]
	v_mov_b32_dpp v180, v146 row_ror:2 row_mask:0xf bank_mask:0xf
	v_mov_b32_dpp v180, v152 row_shr:2 row_mask:0xf bank_mask:0xf
	v_mov_b32_dpp v181, v147 row_ror:2 row_mask:0xf bank_mask:0xf
	v_mov_b32_dpp v181, v153 row_shr:2 row_mask:0xf bank_mask:0xf
	v_mov_b32_dpp v182, v146 row_ror:1 row_mask:0xf bank_mask:0xf
	v_mov_b32_dpp v182, v152 row_shr:1 row_mask:0xf bank_mask:0xf
	v_mov_b32_dpp v183, v147 row_ror:1 row_mask:0xf bank_mask:0xf
	v_mov_b32_dpp v183, v153 row_shr:1 row_mask:0xf bank_mask:0xf
	v_mov_b32_dpp v147, v149 row_ror:1 row_mask:0xf bank_mask:0xf
	v_mov_b32_dpp v147, v179 row_shr:1 row_mask:0xf bank_mask:0xf
	v_mov_b32_dpp v149, v149 row_ror:2 row_mask:0xf bank_mask:0xf
	v_mov_b32_dpp v149, v179 row_shr:2 row_mask:0xf bank_mask:0xf
	v_mov_b32_dpp v146, v148 row_ror:1 row_mask:0xf bank_mask:0xf
	v_mov_b32_dpp v146, v178 row_shr:1 row_mask:0xf bank_mask:0xf
	v_mov_b32_dpp v148, v148 row_ror:2 row_mask:0xf bank_mask:0xf
	v_mov_b32_dpp v148, v178 row_shr:2 row_mask:0xf bank_mask:0xf
	s_waitcnt lgkmcnt(5)
	v_pk_fma_f32 v[148:149], v[130:131], v[148:149], v[142:143]
	s_waitcnt lgkmcnt(3)
	v_pk_fma_f32 v[180:181], v[132:133], v[180:181], v[144:145]
	s_waitcnt lgkmcnt(2)
	v_pk_fma_f32 v[146:147], v[138:139], v[146:147], v[148:149]
	s_waitcnt lgkmcnt(0)
	v_pk_fma_f32 v[148:149], v[140:141], v[182:183], v[180:181]
	v_pk_fma_f32 v[146:147], v[134:135], v[178:179], v[146:147]
	v_pk_fma_f32 v[148:149], v[136:137], v[152:153], v[148:149]
	v_mul_f32_e32 v151, 0xbfb8aa3b, v146
	v_mul_f32_e32 v180, 0xbfb8aa3b, v147
	v_mul_f32_e32 v181, 0xbfb8aa3b, v148
	v_mul_f32_e32 v182, 0xbfb8aa3b, v149
	v_exp_f32_e32 v151, v151
	v_exp_f32_e32 v180, v180
	v_exp_f32_e32 v181, v181
	v_exp_f32_e32 v182, v182
	v_add_f32_e32 v151, 1.0, v151
	v_add_f32_e32 v183, 1.0, v180
	v_add_f32_e32 v193, 1.0, v181
	v_add_f32_e32 v197, 1.0, v182
	v_rcp_f32_e32 v180, v151
	v_rcp_f32_e32 v181, v183
	v_rcp_f32_e32 v182, v193
	v_rcp_f32_e32 v183, v197
	v_pk_mul_f32 v[198:199], v[100:101], v[150:151] op_sel_hi:[1,0]
	v_pk_mul_f32 v[150:151], v[98:99], v[150:151] op_sel_hi:[1,0]
	v_pk_mul_f32 v[146:147], v[146:147], v[180:181]
	v_pk_mul_f32 v[148:149], v[148:149], v[182:183]
	v_pk_mul_f32 v[146:147], v[150:151], v[146:147]
	v_pk_mul_f32 v[148:149], v[198:199], v[148:149]
	v_cvt_pk_bf16_f32 v146, v146, v147
	v_cvt_pk_bf16_f32 v147, v148, v149
	global_store_dwordx2 v187, v[146:147], s[46:47]
	v_mov_b32_e32 v187, v97
	v_add_lshl_u32 v193, v220, v196, 1
	v_mov_b32_e32 v146, v238
	v_pk_mul_f32 v[150:151], v[90:91], v[146:147] op_sel_hi:[1,0]
	v_pk_mul_f32 v[180:181], v[88:89], v[146:147] op_sel_hi:[1,0]
	v_mov_b32_dpp v149, v179 row_ror:1 row_mask:0xf bank_mask:0xf
	s_nop 0
	v_mov_b32_dpp v149, v181 row_shr:1 row_mask:0xf bank_mask:0xf
	v_mov_b32_dpp v148, v178 row_ror:1 row_mask:0xf bank_mask:0xf
	v_mov_b32_dpp v148, v180 row_shr:1 row_mask:0xf bank_mask:0xf
	v_mov_b32_dpp v182, v152 row_ror:1 row_mask:0xf bank_mask:0xf
	v_mov_b32_dpp v182, v150 row_shr:1 row_mask:0xf bank_mask:0xf
	v_mov_b32_dpp v183, v153 row_ror:1 row_mask:0xf bank_mask:0xf
	v_mov_b32_dpp v183, v151 row_shr:1 row_mask:0xf bank_mask:0xf
	v_mov_b32_dpp v246, v178 row_ror:2 row_mask:0xf bank_mask:0xf
	v_mov_b32_dpp v246, v180 row_shr:2 row_mask:0xf bank_mask:0xf
	v_mov_b32_dpp v178, v152 row_ror:2 row_mask:0xf bank_mask:0xf
	v_mov_b32_dpp v178, v150 row_shr:2 row_mask:0xf bank_mask:0xf
	v_mov_b32_e32 v152, v246
	v_mov_b32_dpp v247, v179 row_ror:2 row_mask:0xf bank_mask:0xf
	v_mov_b32_dpp v247, v181 row_shr:2 row_mask:0xf bank_mask:0xf
	v_mov_b32_dpp v179, v153 row_ror:2 row_mask:0xf bank_mask:0xf
	v_mov_b32_dpp v179, v151 row_shr:2 row_mask:0xf bank_mask:0xf
	v_mov_b32_e32 v153, v247
	s_waitcnt lgkmcnt(5)
	v_pk_fma_f32 v[152:153], v[130:131], v[152:153], v[142:143]
	s_waitcnt lgkmcnt(3)
	v_pk_fma_f32 v[178:179], v[132:133], v[178:179], v[144:145]
	s_waitcnt lgkmcnt(2)
	v_pk_fma_f32 v[148:149], v[138:139], v[148:149], v[152:153]
	v_lshl_add_u64 v[184:185], s[48:49], 0, v[186:187]
	s_waitcnt lgkmcnt(0)
; DI unsigned pk2(float lo, float hi) { f32x2 v = {lo, hi}; bf16x2_t b = __builtin_convertvector(v, bf16x2_t); return __builtin_bit_cast(unsigned, b); }
; DI float silu_f(float x) { return x * __builtin_amdgcn_rcpf(1.f + __builtin_amdgcn_exp2f(-LOG2E * x)); }
; DI float rstd_of(float ssq, float inv_n) { return 1.0f / sqrtf(ssq * inv_n + EPS); }
; DI float acc_get_i(const acc_t* base, unsigned idx, float inv_scale) { return (float)(*(const acc_t*)((const char*)base + idx * 8u)) * inv_scale; }
; template <class T> DI T* boff(T* base, unsigned byte_off) { return (T*)((char*)base + byte_off); }
;     DI void operator()(const f32x4 (&acc)[2][2][4][2], const Unit& u, int wr, int wc, int fr, int fq) const {
;     ...
;                 for (int m = 0; m < 4; ++m) { const int row = u.pm * BM + ai * HALF + wr * 64 + m * 16 + fr;
;                     const float rs = rstd_of(acc_get_i(ssq, (unsigned)row, 1.0f / SSQ_SCALE), 1.0f / DM);
;                     const f32x4 g = acc[ai][0][m][n] * rs, up = acc[ai][1][m][n] * rs;
;                     f32x4 a;
; #pragma unroll
;                     for (int j = 0; j < 4; ++j) { const float s1 = __shfl(fr == 15 ? pg[j] : g[j], src1), s2 = __shfl(fr >= 14 ? pg[j] : g[j], src2);
;                         a[j] = silu_f(cbv[j] + w0[j] * s2 + w1[j] * s1 + w2[j] * g[j]) * up[j]; }
;                     u32x2 gw; gw.x = pk2(g[0], g[1]); gw.y = pk2(g[2], g[3]);
;                     if (m == 0 && fr < 2) {
;                         *boff((u32x2*)GS, (unsigned)(((row >> 6) * 4 + 2 + fr) * DFF + c4) * 2u) = gw;
;                         u32x2 uw; uw.x = pk2(up[0], up[1]); uw.y = pk2(up[2], up[3]); *boff((u32x2*)US, (unsigned)(((row >> 6) * 2 + fr) * DFF + c4) * 2u) = uw;
;                     } else { u32x2 w; w.x = pk2(a[0], a[1]); w.y = pk2(a[2], a[3]); *boff((u32x2*)A2, (unsigned)(row * DFF + c4) * 2u) = w; }
;                     if (m == 3 && fr >= 14) {
;                         *boff((u32x2*)GS, (unsigned)(((row >> 6) * 4 + (fr - 14)) * DFF + c4) * 2u) = gw;
;                         if ((row & (SEQ - 1)) >= SEQ - 2) *boff((f32x4*)fcp, (unsigned)(((row >> 11) * 2 + ((row & (SEQ - 1)) - (SEQ - 2))) * DFF + c4) * 4u) = g;
;                     }
	v_pk_fma_f32 v[152:153], v[140:141], v[182:183], v[178:179]
	v_pk_fma_f32 v[148:149], v[134:135], v[180:181], v[148:149]
	v_pk_fma_f32 v[152:153], v[136:137], v[150:151], v[152:153]
	v_mul_f32_e32 v147, 0xbfb8aa3b, v148
	v_mul_f32_e32 v178, 0xbfb8aa3b, v149
	v_mul_f32_e32 v179, 0xbfb8aa3b, v152
	v_mul_f32_e32 v182, 0xbfb8aa3b, v153
	v_exp_f32_e32 v147, v147
	v_exp_f32_e32 v178, v178
	v_exp_f32_e32 v179, v179
	v_exp_f32_e32 v182, v182
	v_add_f32_e32 v147, 1.0, v147
	v_add_f32_e32 v183, 1.0, v178
	v_add_f32_e32 v186, 1.0, v179
	v_add_f32_e32 v187, 1.0, v182
	v_rcp_f32_e32 v178, v147
	v_rcp_f32_e32 v179, v183
	v_rcp_f32_e32 v182, v186
	v_rcp_f32_e32 v183, v187
	v_pk_mul_f32 v[186:187], v[82:83], v[146:147] op_sel_hi:[1,0]
	v_pk_mul_f32 v[146:147], v[80:81], v[146:147] op_sel_hi:[1,0]
	v_pk_mul_f32 v[148:149], v[148:149], v[178:179]
	v_pk_mul_f32 v[152:153], v[152:153], v[182:183]
	v_pk_mul_f32 v[146:147], v[146:147], v[148:149]
	v_pk_mul_f32 v[148:149], v[186:187], v[152:153]
	v_cvt_pk_bf16_f32 v146, v146, v147
	v_cvt_pk_bf16_f32 v147, v148, v149
	global_store_dwordx2 v193, v[146:147], s[46:47]
	v_mov_b32_e32 v152, v239
	v_pk_mul_f32 v[148:149], v[74:75], v[152:153] op_sel_hi:[1,0]
	v_pk_mul_f32 v[146:147], v[72:73], v[152:153] op_sel_hi:[1,0]
	v_mov_b32_dpp v178, v180 row_ror:2 row_mask:0xf bank_mask:0xf
	s_nop 0
	v_mov_b32_dpp v178, v146 row_shr:2 row_mask:0xf bank_mask:0xf
	v_mov_b32_dpp v179, v181 row_ror:2 row_mask:0xf bank_mask:0xf
	v_mov_b32_dpp v179, v147 row_shr:2 row_mask:0xf bank_mask:0xf
	v_mov_b32_dpp v182, v150 row_ror:1 row_mask:0xf bank_mask:0xf
	v_mov_b32_dpp v182, v148 row_shr:1 row_mask:0xf bank_mask:0xf
	v_mov_b32_dpp v183, v151 row_ror:1 row_mask:0xf bank_mask:0xf
	v_mov_b32_dpp v183, v149 row_shr:1 row_mask:0xf bank_mask:0xf
	v_mov_b32_dpp v246, v181 row_ror:1 row_mask:0xf bank_mask:0xf
	v_mov_b32_dpp v246, v147 row_shr:1 row_mask:0xf bank_mask:0xf
	v_mov_b32_dpp v181, v151 row_ror:2 row_mask:0xf bank_mask:0xf
	v_mov_b32_dpp v181, v149 row_shr:2 row_mask:0xf bank_mask:0xf
	v_mov_b32_e32 v151, v246
	v_mov_b32_dpp v247, v150 row_ror:2 row_mask:0xf bank_mask:0xf
	v_mov_b32_dpp v247, v148 row_shr:2 row_mask:0xf bank_mask:0xf
	v_mov_b32_dpp v150, v180 row_ror:1 row_mask:0xf bank_mask:0xf
	v_mov_b32_dpp v150, v146 row_shr:1 row_mask:0xf bank_mask:0xf
	v_mov_b32_e32 v180, v247
	s_waitcnt lgkmcnt(5)
	v_pk_fma_f32 v[178:179], v[130:131], v[178:179], v[142:143]
	s_waitcnt lgkmcnt(3)
	v_pk_fma_f32 v[180:181], v[132:133], v[180:181], v[144:145]
	s_waitcnt lgkmcnt(2)
	v_pk_fma_f32 v[150:151], v[138:139], v[150:151], v[178:179]
	s_waitcnt lgkmcnt(0)
	v_pk_fma_f32 v[178:179], v[140:141], v[182:183], v[180:181]
	v_pk_fma_f32 v[150:151], v[134:135], v[146:147], v[150:151]
	v_pk_fma_f32 v[178:179], v[136:137], v[148:149], v[178:179]
	v_mul_f32_e32 v153, 0xbfb8aa3b, v150
	v_mul_f32_e32 v180, 0xbfb8aa3b, v151
	v_mul_f32_e32 v181, 0xbfb8aa3b, v178
	v_mul_f32_e32 v182, 0xbfb8aa3b, v179
	v_exp_f32_e32 v153, v153
	v_exp_f32_e32 v180, v180
	v_exp_f32_e32 v181, v181
	v_exp_f32_e32 v182, v182
	v_add_f32_e32 v153, 1.0, v153
	v_add_f32_e32 v183, 1.0, v180
	v_add_f32_e32 v184, 1.0, v181
	v_add_f32_e32 v185, 1.0, v182
	v_rcp_f32_e32 v180, v153
	v_rcp_f32_e32 v181, v183
	v_rcp_f32_e32 v182, v184
	v_rcp_f32_e32 v183, v185
	v_pk_mul_f32 v[184:185], v[66:67], v[152:153] op_sel_hi:[1,0]
	v_pk_mul_f32 v[152:153], v[64:65], v[152:153] op_sel_hi:[1,0]
	v_pk_mul_f32 v[150:151], v[150:151], v[180:181]
	v_pk_mul_f32 v[178:179], v[178:179], v[182:183]
	v_pk_mul_f32 v[150:151], v[152:153], v[150:151]
	v_pk_mul_f32 v[152:153], v[184:185], v[178:179]
	v_cvt_pk_bf16_f32 v150, v150, v151
	v_cvt_pk_bf16_f32 v151, v152, v153
	v_add_lshl_u32 v152, v230, v196, 1
	global_store_dwordx2 v152, v[150:151], s[46:47]
	s_and_saveexec_b64 s[0:1], s[38:39]
	s_cbranch_execz .LBB0_3114
	s_movk_i32 s2, 0x7fd
	v_add_lshl_u32 v152, v217, v196, 1
	v_cvt_pk_bf16_f32 v150, v146, v147
	v_cvt_pk_bf16_f32 v151, v148, v149
	v_cmp_lt_u32_e32 vcc, s2, v189
	global_store_dwordx2 v152, v[150:151], s[50:51]
	s_and_b64 exec, exec, vcc
	s_cbranch_execz .LBB0_3114
	v_add_u32_e32 v150, s14, v189
	v_mul_lo_u32 v150, v150, s90
	v_add_lshl_u32 v150, v150, v196, 2
	global_store_dwordx4 v150, v[146:149], s[58:59]
.LBB0_3114:
	s_or_b64 exec, exec, s[0:1]
	v_mov_b32_e32 v189, v97
	v_lshl_add_u64 v[146:147], s[48:49], 0, v[188:189]
	v_mov_b32_e32 v150, v240
	v_pk_mul_f32 v[148:149], v[56:57], v[150:151] op_sel_hi:[1,0]
	v_pk_mul_f32 v[146:147], v[58:59], v[150:151] op_sel_hi:[1,0]
	v_pk_mul_f32 v[178:179], v[50:51], v[150:151] op_sel_hi:[1,0]
	v_pk_mul_f32 v[180:181], v[48:49], v[150:151] op_sel_hi:[1,0]
	v_mov_b32_e32 v182, 0
	v_mov_b32_dpp v182, v148 row_shr:1 row_mask:0xf bank_mask:0xf
	v_mov_b32_e32 v186, 0
	v_mov_b32_dpp v186, v148 row_shr:2 row_mask:0xf bank_mask:0xf
	v_mov_b32_e32 v183, 0
	v_mov_b32_dpp v183, v149 row_shr:1 row_mask:0xf bank_mask:0xf
	v_mov_b32_e32 v187, 0
	v_mov_b32_dpp v187, v149 row_shr:2 row_mask:0xf bank_mask:0xf
	v_mov_b32_e32 v184, 0
	v_mov_b32_dpp v184, v146 row_shr:1 row_mask:0xf bank_mask:0xf
	v_mov_b32_e32 v188, 0
	v_mov_b32_dpp v188, v146 row_shr:2 row_mask:0xf bank_mask:0xf
	v_mov_b32_e32 v185, 0
	v_mov_b32_dpp v185, v147 row_shr:1 row_mask:0xf bank_mask:0xf
	v_mov_b32_e32 v189, 0
	v_mov_b32_dpp v189, v147 row_shr:2 row_mask:0xf bank_mask:0xf
	s_and_saveexec_b64 s[0:1], s[40:41]
	s_xor_b64 s[0:1], exec, s[0:1]
	s_cbranch_execz .LBB0_3116
	s_waitcnt lgkmcnt(4)
	v_pk_fma_f32 v[150:151], v[130:131], v[186:187], v[142:143]
	s_nop 0
	v_pk_fma_f32 v[150:151], v[138:139], v[182:183], v[150:151]
	s_waitcnt lgkmcnt(0)
	v_pk_fma_f32 v[182:183], v[132:133], v[188:189], v[144:145]
	v_pk_fma_f32 v[150:151], v[134:135], v[148:149], v[150:151]
	v_pk_fma_f32 v[182:183], v[140:141], v[184:185], v[182:183]
	v_mul_f32_e32 v96, 0xbfb8aa3b, v150
	v_exp_f32_e32 v96, v96
	v_mul_f32_e32 v152, 0xbfb8aa3b, v151
	v_exp_f32_e32 v152, v152
	v_pk_fma_f32 v[182:183], v[136:137], v[146:147], v[182:183]
	v_add_f32_e32 v96, 1.0, v96
	v_mul_f32_e32 v184, 0xbfb8aa3b, v183
	v_add_f32_e32 v153, 1.0, v152
	v_rcp_f32_e32 v152, v96
	v_mul_f32_e32 v96, 0xbfb8aa3b, v182
	v_exp_f32_e32 v96, v96
	v_exp_f32_e32 v185, v184
	v_rcp_f32_e32 v153, v153
	v_add_f32_e32 v96, 1.0, v96
	v_rcp_f32_e32 v184, v96
	v_add_f32_e32 v96, 1.0, v185
	v_rcp_f32_e32 v185, v96
	v_pk_mul_f32 v[150:151], v[150:151], v[152:153]
	v_add_lshl_u32 v96, v231, v196, 1
	v_pk_mul_f32 v[150:151], v[180:181], v[150:151]
	v_pk_mul_f32 v[152:153], v[182:183], v[184:185]
	v_cvt_pk_bf16_f32 v150, v150, v151
	v_pk_mul_f32 v[152:153], v[178:179], v[152:153]
	s_nop 0
	v_cvt_pk_bf16_f32 v151, v152, v153
	global_store_dwordx2 v96, v[150:151], s[46:47]

; DI unsigned pk2(float lo, float hi) { f32x2 v = {lo, hi}; bf16x2_t b = __builtin_convertvector(v, bf16x2_t); return __builtin_bit_cast(unsigned, b); }
; DI float silu_f(float x) { return x * __builtin_amdgcn_rcpf(1.f + __builtin_amdgcn_exp2f(-LOG2E * x)); }
; DI float rstd_of(float ssq, float inv_n) { return 1.0f / sqrtf(ssq * inv_n + EPS); }
; DI float acc_get_i(const acc_t* base, unsigned idx, float inv_scale) { return (float)(*(const acc_t*)((const char*)base + idx * 8u)) * inv_scale; }
; template <class T> DI T* boff(T* base, unsigned byte_off) { return (T*)((char*)base + byte_off); }
;     DI void operator()(const f32x4 (&acc)[2][2][4][2], const Unit& u, int wr, int wc, int fr, int fq) const {
;     ...
;                 for (int m = 0; m < 4; ++m) { const int row = u.pm * BM + ai * HALF + wr * 64 + m * 16 + fr;
;                     const float rs = rstd_of(acc_get_i(ssq, (unsigned)row, 1.0f / SSQ_SCALE), 1.0f / DM);
;                     const f32x4 g = acc[ai][0][m][n] * rs, up = acc[ai][1][m][n] * rs;
;                     f32x4 a;
; #pragma unroll
;                     for (int j = 0; j < 4; ++j) { const float s1 = __shfl(fr == 15 ? pg[j] : g[j], src1), s2 = __shfl(fr >= 14 ? pg[j] : g[j], src2);
;                         a[j] = silu_f(cbv[j] + w0[j] * s2 + w1[j] * s1 + w2[j] * g[j]) * up[j]; }
;                     u32x2 gw; gw.x = pk2(g[0], g[1]); gw.y = pk2(g[2], g[3]);
;                     if (m == 0 && fr < 2) {
;                         *boff((u32x2*)GS, (unsigned)(((row >> 6) * 4 + 2 + fr) * DFF + c4) * 2u) = gw;
;                         u32x2 uw; uw.x = pk2(up[0], up[1]); uw.y = pk2(up[2], up[3]); *boff((u32x2*)US, (unsigned)(((row >> 6) * 2 + fr) * DFF + c4) * 2u) = uw;
;                     } else { u32x2 w; w.x = pk2(a[0], a[1]); w.y = pk2(a[2], a[3]); *boff((u32x2*)A2, (unsigned)(row * DFF + c4) * 2u) = w; }
;                     if (m == 3 && fr >= 14) {
;                         *boff((u32x2*)GS, (unsigned)(((row >> 6) * 4 + (fr - 14)) * DFF + c4) * 2u) = gw;
;                         if ((row & (SEQ - 1)) >= SEQ - 2) *boff((f32x4*)fcp, (unsigned)(((row >> 11) * 2 + ((row & (SEQ - 1)) - (SEQ - 2))) * DFF + c4) * 4u) = g;
;                     }
.LBB0_3118:
	s_or_b64 exec, exec, s[0:1]
	v_mov_b32_e32 v191, v97
	v_lshl_add_u64 v[150:151], s[48:49], 0, v[190:191]
	s_waitcnt lgkmcnt(2)
	v_add_lshl_u32 v188, v195, v196, 1
	v_mov_b32_e32 v193, v97
	v_mov_b32_e32 v195, v97
	v_mov_b32_e32 v96, v241
	v_pk_mul_f32 v[150:151], v[42:43], v[96:97] op_sel_hi:[1,0]
	v_pk_mul_f32 v[152:153], v[40:41], v[96:97] op_sel_hi:[1,0]
	v_mov_b32_dpp v178, v146 row_ror:2 row_mask:0xf bank_mask:0xf
	v_mov_b32_dpp v178, v150 row_shr:2 row_mask:0xf bank_mask:0xf
	v_mov_b32_dpp v179, v147 row_ror:2 row_mask:0xf bank_mask:0xf
	v_mov_b32_dpp v179, v151 row_shr:2 row_mask:0xf bank_mask:0xf
	v_mov_b32_dpp v180, v146 row_ror:1 row_mask:0xf bank_mask:0xf
	v_mov_b32_dpp v180, v150 row_shr:1 row_mask:0xf bank_mask:0xf
	v_mov_b32_dpp v181, v147 row_ror:1 row_mask:0xf bank_mask:0xf
	v_mov_b32_dpp v181, v151 row_shr:1 row_mask:0xf bank_mask:0xf
	v_mov_b32_dpp v146, v148 row_ror:1 row_mask:0xf bank_mask:0xf
	v_mov_b32_dpp v146, v152 row_shr:1 row_mask:0xf bank_mask:0xf
	v_mov_b32_dpp v148, v148 row_ror:2 row_mask:0xf bank_mask:0xf
	v_mov_b32_dpp v148, v152 row_shr:2 row_mask:0xf bank_mask:0xf
	v_mov_b32_dpp v147, v149 row_ror:1 row_mask:0xf bank_mask:0xf
	v_mov_b32_dpp v147, v153 row_shr:1 row_mask:0xf bank_mask:0xf
	v_mov_b32_dpp v149, v149 row_ror:2 row_mask:0xf bank_mask:0xf
	v_mov_b32_dpp v149, v153 row_shr:2 row_mask:0xf bank_mask:0xf
	s_waitcnt lgkmcnt(4)
	v_pk_fma_f32 v[148:149], v[130:131], v[148:149], v[142:143]
	v_pk_mul_f32 v[184:185], v[34:35], v[96:97] op_sel_hi:[1,0]
	s_waitcnt lgkmcnt(2)
	v_pk_fma_f32 v[178:179], v[132:133], v[178:179], v[144:145]
	v_pk_fma_f32 v[146:147], v[138:139], v[146:147], v[148:149]
	s_waitcnt lgkmcnt(0)
	v_pk_fma_f32 v[148:149], v[140:141], v[180:181], v[178:179]
	v_pk_fma_f32 v[146:147], v[134:135], v[152:153], v[146:147]
	v_pk_fma_f32 v[148:149], v[136:137], v[150:151], v[148:149]
	v_mul_f32_e32 v178, 0xbfb8aa3b, v146
	v_mul_f32_e32 v179, 0xbfb8aa3b, v147
	v_mul_f32_e32 v180, 0xbfb8aa3b, v148
	v_mul_f32_e32 v181, 0xbfb8aa3b, v149
	v_exp_f32_e32 v178, v178
	v_exp_f32_e32 v179, v179
	v_exp_f32_e32 v180, v180
	v_exp_f32_e32 v181, v181
	v_add_f32_e32 v178, 1.0, v178
	v_add_f32_e32 v179, 1.0, v179
	v_add_f32_e32 v180, 1.0, v180
	v_add_f32_e32 v181, 1.0, v181
	v_rcp_f32_e32 v178, v178
	v_rcp_f32_e32 v179, v179
	v_rcp_f32_e32 v180, v180
	v_rcp_f32_e32 v181, v181
	v_pk_mul_f32 v[186:187], v[32:33], v[96:97] op_sel_hi:[1,0]
	v_pk_mul_f32 v[146:147], v[146:147], v[178:179]
	v_lshl_add_u64 v[182:183], s[48:49], 0, v[192:193]
	v_pk_mul_f32 v[148:149], v[148:149], v[180:181]
	v_pk_mul_f32 v[146:147], v[186:187], v[146:147]
	v_pk_mul_f32 v[148:149], v[184:185], v[148:149]
	v_cvt_pk_bf16_f32 v146, v146, v147
	v_cvt_pk_bf16_f32 v147, v148, v149
	global_store_dwordx2 v188, v[146:147], s[46:47]
	v_add_lshl_u32 v188, v233, v196, 1
	v_mov_b32_e32 v96, v242
	v_pk_mul_f32 v[178:179], v[26:27], v[96:97] op_sel_hi:[1,0]
	v_pk_mul_f32 v[180:181], v[24:25], v[96:97] op_sel_hi:[1,0]
	v_mov_b32_dpp v148, v152 row_ror:2 row_mask:0xf bank_mask:0xf
	s_nop 0
	v_mov_b32_dpp v148, v180 row_shr:2 row_mask:0xf bank_mask:0xf
	v_mov_b32_dpp v147, v153 row_ror:1 row_mask:0xf bank_mask:0xf
	v_mov_b32_dpp v147, v181 row_shr:1 row_mask:0xf bank_mask:0xf
	v_mov_b32_dpp v149, v153 row_ror:2 row_mask:0xf bank_mask:0xf
	v_mov_b32_dpp v149, v181 row_shr:2 row_mask:0xf bank_mask:0xf
	v_mov_b32_dpp v146, v152 row_ror:1 row_mask:0xf bank_mask:0xf
	v_mov_b32_dpp v146, v180 row_shr:1 row_mask:0xf bank_mask:0xf
	v_mov_b32_dpp v152, v150 row_ror:1 row_mask:0xf bank_mask:0xf
	v_mov_b32_dpp v152, v178 row_shr:1 row_mask:0xf bank_mask:0xf
	v_mov_b32_dpp v153, v151 row_ror:1 row_mask:0xf bank_mask:0xf
	v_mov_b32_dpp v153, v179 row_shr:1 row_mask:0xf bank_mask:0xf
	v_mov_b32_dpp v150, v150 row_ror:2 row_mask:0xf bank_mask:0xf
	v_mov_b32_dpp v150, v178 row_shr:2 row_mask:0xf bank_mask:0xf
	v_mov_b32_dpp v151, v151 row_ror:2 row_mask:0xf bank_mask:0xf
	v_mov_b32_dpp v151, v179 row_shr:2 row_mask:0xf bank_mask:0xf
	s_waitcnt lgkmcnt(5)
	v_pk_fma_f32 v[148:149], v[130:131], v[148:149], v[142:143]
	s_waitcnt lgkmcnt(3)
	v_pk_fma_f32 v[150:151], v[132:133], v[150:151], v[144:145]
	s_waitcnt lgkmcnt(2)
; DI unsigned pk2(float lo, float hi) { f32x2 v = {lo, hi}; bf16x2_t b = __builtin_convertvector(v, bf16x2_t); return __builtin_bit_cast(unsigned, b); }
; DI float silu_f(float x) { return x * __builtin_amdgcn_rcpf(1.f + __builtin_amdgcn_exp2f(-LOG2E * x)); }
; DI float rstd_of(float ssq, float inv_n) { return 1.0f / sqrtf(ssq * inv_n + EPS); }
; DI float acc_get_i(const acc_t* base, unsigned idx, float inv_scale) { return (float)(*(const acc_t*)((const char*)base + idx * 8u)) * inv_scale; }
; template <class T> DI T* boff(T* base, unsigned byte_off) { return (T*)((char*)base + byte_off); }
;     DI void operator()(const f32x4 (&acc)[2][2][4][2], const Unit& u, int wr, int wc, int fr, int fq) const {
;     ...
;                 for (int m = 0; m < 4; ++m) { const int row = u.pm * BM + ai * HALF + wr * 64 + m * 16 + fr;
;                     const float rs = rstd_of(acc_get_i(ssq, (unsigned)row, 1.0f / SSQ_SCALE), 1.0f / DM);
;                     const f32x4 g = acc[ai][0][m][n] * rs, up = acc[ai][1][m][n] * rs;
;                     f32x4 a;
; #pragma unroll
;                     for (int j = 0; j < 4; ++j) { const float s1 = __shfl(fr == 15 ? pg[j] : g[j], src1), s2 = __shfl(fr >= 14 ? pg[j] : g[j], src2);
;                         a[j] = silu_f(cbv[j] + w0[j] * s2 + w1[j] * s1 + w2[j] * g[j]) * up[j]; }
;                     u32x2 gw; gw.x = pk2(g[0], g[1]); gw.y = pk2(g[2], g[3]);
;                     if (m == 0 && fr < 2) {
;                         *boff((u32x2*)GS, (unsigned)(((row >> 6) * 4 + 2 + fr) * DFF + c4) * 2u) = gw;
;                         u32x2 uw; uw.x = pk2(up[0], up[1]); uw.y = pk2(up[2], up[3]); *boff((u32x2*)US, (unsigned)(((row >> 6) * 2 + fr) * DFF + c4) * 2u) = uw;
;                     } else { u32x2 w; w.x = pk2(a[0], a[1]); w.y = pk2(a[2], a[3]); *boff((u32x2*)A2, (unsigned)(row * DFF + c4) * 2u) = w; }
;                     if (m == 3 && fr >= 14) {
;                         *boff((u32x2*)GS, (unsigned)(((row >> 6) * 4 + (fr - 14)) * DFF + c4) * 2u) = gw;
;                         if ((row & (SEQ - 1)) >= SEQ - 2) *boff((f32x4*)fcp, (unsigned)(((row >> 11) * 2 + ((row & (SEQ - 1)) - (SEQ - 2))) * DFF + c4) * 4u) = g;
;                     }
	v_pk_fma_f32 v[146:147], v[138:139], v[146:147], v[148:149]
	v_pk_mul_f32 v[184:185], v[18:19], v[96:97] op_sel_hi:[1,0]
	s_waitcnt lgkmcnt(0)
	v_pk_fma_f32 v[148:149], v[140:141], v[152:153], v[150:151]
	v_pk_fma_f32 v[146:147], v[134:135], v[180:181], v[146:147]
	v_pk_fma_f32 v[148:149], v[136:137], v[178:179], v[148:149]
	v_mul_f32_e32 v150, 0xbfb8aa3b, v146
	v_mul_f32_e32 v151, 0xbfb8aa3b, v147
	v_mul_f32_e32 v152, 0xbfb8aa3b, v148
	v_mul_f32_e32 v153, 0xbfb8aa3b, v149
	v_exp_f32_e32 v150, v150
	v_exp_f32_e32 v151, v151
	v_exp_f32_e32 v152, v152
	v_exp_f32_e32 v153, v153
	v_add_f32_e32 v150, 1.0, v150
	v_add_f32_e32 v151, 1.0, v151
	v_add_f32_e32 v152, 1.0, v152
	v_add_f32_e32 v153, 1.0, v153
	v_rcp_f32_e32 v150, v150
	v_rcp_f32_e32 v151, v151
	v_rcp_f32_e32 v152, v152
	v_rcp_f32_e32 v153, v153
	v_pk_mul_f32 v[186:187], v[16:17], v[96:97] op_sel_hi:[1,0]
	v_pk_mul_f32 v[146:147], v[146:147], v[150:151]
	v_lshl_add_u64 v[182:183], s[48:49], 0, v[194:195]
	v_pk_mul_f32 v[148:149], v[148:149], v[152:153]
	v_pk_mul_f32 v[146:147], v[186:187], v[146:147]
	v_pk_mul_f32 v[148:149], v[184:185], v[148:149]
	v_cvt_pk_bf16_f32 v146, v146, v147
	v_cvt_pk_bf16_f32 v147, v148, v149
	global_store_dwordx2 v188, v[146:147], s[46:47]
	v_mov_b32_e32 v96, v243
	v_pk_mul_f32 v[148:149], v[10:11], v[96:97] op_sel_hi:[1,0]
	v_pk_mul_f32 v[146:147], v[8:9], v[96:97] op_sel_hi:[1,0]
	v_mov_b32_dpp v152, v180 row_ror:2 row_mask:0xf bank_mask:0xf
	s_nop 0
	v_mov_b32_dpp v152, v146 row_shr:2 row_mask:0xf bank_mask:0xf
	v_mov_b32_dpp v151, v181 row_ror:1 row_mask:0xf bank_mask:0xf
	v_mov_b32_dpp v151, v147 row_shr:1 row_mask:0xf bank_mask:0xf
	v_mov_b32_dpp v153, v181 row_ror:2 row_mask:0xf bank_mask:0xf
	v_mov_b32_dpp v153, v147 row_shr:2 row_mask:0xf bank_mask:0xf
	v_mov_b32_dpp v150, v180 row_ror:1 row_mask:0xf bank_mask:0xf
	v_mov_b32_dpp v150, v146 row_shr:1 row_mask:0xf bank_mask:0xf
	v_mov_b32_dpp v180, v178 row_ror:1 row_mask:0xf bank_mask:0xf
	v_mov_b32_dpp v180, v148 row_shr:1 row_mask:0xf bank_mask:0xf
	v_mov_b32_dpp v181, v179 row_ror:1 row_mask:0xf bank_mask:0xf
	v_mov_b32_dpp v181, v149 row_shr:1 row_mask:0xf bank_mask:0xf
	v_mov_b32_dpp v178, v178 row_ror:2 row_mask:0xf bank_mask:0xf
	v_mov_b32_dpp v178, v148 row_shr:2 row_mask:0xf bank_mask:0xf
	v_mov_b32_dpp v179, v179 row_ror:2 row_mask:0xf bank_mask:0xf
	v_mov_b32_dpp v179, v149 row_shr:2 row_mask:0xf bank_mask:0xf
	s_waitcnt lgkmcnt(5)
	v_pk_fma_f32 v[130:131], v[130:131], v[152:153], v[142:143]
	s_waitcnt lgkmcnt(3)
	v_pk_fma_f32 v[132:133], v[132:133], v[178:179], v[144:145]
	s_waitcnt lgkmcnt(2)
	v_pk_fma_f32 v[130:131], v[138:139], v[150:151], v[130:131]
	v_pk_mul_f32 v[138:139], v[2:3], v[96:97] op_sel_hi:[1,0]
	s_waitcnt lgkmcnt(0)
	v_pk_fma_f32 v[132:133], v[140:141], v[180:181], v[132:133]
	v_pk_fma_f32 v[130:131], v[134:135], v[146:147], v[130:131]
	v_pk_fma_f32 v[132:133], v[136:137], v[148:149], v[132:133]
	v_mul_f32_e32 v134, 0xbfb8aa3b, v130
	v_mul_f32_e32 v135, 0xbfb8aa3b, v131
	v_mul_f32_e32 v136, 0xbfb8aa3b, v132
	v_mul_f32_e32 v137, 0xbfb8aa3b, v133
	v_exp_f32_e32 v134, v134
	v_exp_f32_e32 v135, v135
	v_exp_f32_e32 v136, v136
	v_exp_f32_e32 v137, v137
	v_add_f32_e32 v134, 1.0, v134
	v_add_f32_e32 v135, 1.0, v135
	v_add_f32_e32 v136, 1.0, v136
	v_add_f32_e32 v137, 1.0, v137
	v_rcp_f32_e32 v134, v134
	v_rcp_f32_e32 v135, v135
	v_rcp_f32_e32 v136, v136
	v_rcp_f32_e32 v137, v137
	v_pk_mul_f32 v[140:141], v[0:1], v[96:97] op_sel_hi:[1,0]
	v_pk_mul_f32 v[130:131], v[130:131], v[134:135]
	v_add_lshl_u32 v96, v234, v196, 1
	v_pk_mul_f32 v[132:133], v[132:133], v[136:137]
	v_pk_mul_f32 v[130:131], v[140:141], v[130:131]
	v_pk_mul_f32 v[132:133], v[138:139], v[132:133]
	v_cvt_pk_bf16_f32 v130, v130, v131
	v_cvt_pk_bf16_f32 v131, v132, v133
	global_store_dwordx2 v96, v[130:131], s[46:47]
	s_and_saveexec_b64 s[0:1], s[38:39]
	s_cbranch_execz .LBB0_3121
	s_movk_i32 s2, 0x7fd
	v_add_lshl_u32 v96, v221, v196, 1
	v_cvt_pk_bf16_f32 v130, v146, v147
	v_cvt_pk_bf16_f32 v131, v148, v149
	v_cmp_lt_u32_e32 vcc, s2, v235
	global_store_dwordx2 v96, v[130:131], s[50:51]
	s_and_b64 exec, exec, vcc
	s_cbranch_execz .LBB0_3121
	v_add_u32_e32 v96, s15, v235
	v_mul_lo_u32 v96, v96, s90
	v_add_lshl_u32 v96, v96, v196, 2
	global_store_dwordx4 v96, v[146:149], s[58:59]
